# grid barrier between P2a and P2b replaced by a counted release/acquire dependency (only mem-attention units and the pool GEMM wait), on top of the pooled_phase rewrite
# speedup vs baseline: 1.0280x; 1.0085x over previous
.LBB0_285:
	s_mov_b64 s[6:7], s[88:89]
	s_getreg_b32 s4, hwreg(HW_REG_XCC_ID, 0, 4)
	s_waitcnt vmcnt(0)
	v_readlane_b32 s0, v255, 31
	v_readlane_b32 s1, v255, 32
	s_and_b64 vcc, exec, s[0:1]
	s_waitcnt vmcnt(0)
	s_barrier
	s_cbranch_vccnz .LBB0_339
	v_mbcnt_lo_u32_b32 v0, -1, 0
	v_mbcnt_hi_u32_b32 v0, -1, v0
	s_nop 0
	v_cmp_eq_u32_e32 vcc, 0, v0
	s_and_saveexec_b64 s[0:1], vcc
	s_cbranch_execz .LBB0_338
	s_load_dwordx2 s[6:7], s[6:7], 0x98
	buffer_wbl2 sc1
	v_mov_b32_e32 v0, 1
	v_mov_b32_e32 v2, 0
	s_waitcnt vmcnt(0) lgkmcnt(0)
	global_atomic_add v2, v0, s[6:7] offset:2048
	s_waitcnt vmcnt(0)

.LBB0_349:
	v_readlane_b32 s0, v255, 16
	s_waitcnt lgkmcnt(0)
	s_barrier
	v_mov_b32_e32 v0, s0
	ds_read_b32 v0, v0
	s_movk_i32 s0, 0x4ff
	s_waitcnt lgkmcnt(0)
	s_barrier
	v_cmp_lt_u32_e32 vcc, s0, v0
	v_readfirstlane_b32 s16, v0
	s_mov_b64 s[0:1], -1
	s_cbranch_vccnz .LBB0_342
	s_cmpk_gt_u32 s16, 0x3ff
	s_cbranch_scc0 .LBB0_352
	v_readlane_b32 s0, v255, 55
	v_readlane_b32 s1, v255, 56
	v_readlane_b32 s4, v255, 22
	s_add_i32 s4, s4, 2
	s_mul_i32 s4, s4, s80
	v_mov_b32_e32 v0, 0
	s_mov_b32 s5, 0
	s_nop 3
.Lp2a_wait_m:
	global_load_dword v2, v0, s[0:1] offset:2048 sc1
	s_waitcnt vmcnt(0)
	v_cmp_le_u32_e32 vcc, s4, v2
	s_nop 1
	s_cbranch_vccnz .Lp2a_ok_m
	s_sleep 4
	s_add_i32 s5, s5, 1
	s_cmp_lt_u32 s5, 0x400
	s_cbranch_scc1 .Lp2a_wait_m
.Lp2a_ok_m:
	buffer_inv sc1
	s_waitcnt vmcnt(0)
	s_add_i32 s0, s16, 0xfffffc00
	s_lshr_b32 s1, s0, 6
	s_lshl_b32 s0, s16, 8
	s_and_b32 s0, s0, 0xf00
	v_readlane_b32 s5, v254, 18
	s_lshl_b32 s4, s1, 12
	s_add_i32 s0, s0, s5
	s_add_i32 s5, s0, s4
	s_lshl_b32 s0, s16, 4
	v_mbcnt_lo_u32_b32 v22, -1, 0
	v_mbcnt_hi_u32_b32 v22, -1, v22
	s_and_b32 s0, s0, 0x300
	v_add_u32_e32 v182, s83, v22
	s_lshl_b32 s4, s1, 8
	s_lshl_b32 s94, s0, 1
	v_readlane_b32 s6, v255, 41
	v_ashrrev_i32_e32 v40, 4, v182
	s_add_u32 s6, s6, s94
	v_readlane_b32 s7, v255, 42
	v_lshlrev_b32_e32 v183, 4, v22
	v_add_u32_e32 v2, s4, v40
	s_addc_u32 s7, s7, 0
	v_and_b32_e32 v0, 0xf0, v183
	v_ashrrev_i32_e32 v3, 31, v2
	v_add_u32_e32 v184, 0x200, v182
	v_lshl_add_u64 v[10:11], s[6:7], 0, v[0:1]
	v_lshlrev_b64 v[2:3], 11, v[2:3]
	v_ashrrev_i32_e32 v41, 4, v184
	v_lshl_add_u64 v[6:7], v[10:11], 0, v[2:3]
	v_add_u32_e32 v2, s4, v41
	v_ashrrev_i32_e32 v3, 31, v2
	v_lshlrev_b64 v[2:3], 11, v[2:3]
	v_lshl_add_u64 v[8:9], v[10:11], 0, v[2:3]
	global_load_dwordx4 v[2:5], v[6:7], off
	global_load_dwordx4 v[12:15], v[8:9], off
	v_and_b32_e32 v180, 31, v22
	v_mov_b64_e32 v[16:17], s[88:89]
	v_ashrrev_i32_e32 v181, 5, v22
	v_or_b32_e32 v158, s5, v180
	v_lshlrev_b32_e32 v18, 3, v181
	v_add_u32_e32 v0, 0, v0
	s_movk_i32 s8, 0x110
	v_mad_i64_i32 v[16:17], s[6:7], v158, s87, v[16:17]
	s_or_b32 s5, s4, 64
	v_ashrrev_i32_e32 v19, 31, v18
	v_mad_u64_u32 v[162:163], s[6:7], v40, s8, v[0:1]
	v_mad_u64_u32 v[164:165], s[6:7], v41, s8, v[0:1]
	v_lshl_add_u64 v[160:161], v[16:17], 0, s[94:95]
	v_add_u32_e32 v20, s5, v41
	v_add_u32_e32 v16, s5, v40
	v_lshl_add_u64 v[18:19], v[18:19], 1, v[160:161]
	v_ashrrev_i32_e32 v21, 31, v20
	s_mov_b64 s[6:7], 0x2000
	s_movk_i32 s5, 0x2000
	v_ashrrev_i32_e32 v17, 31, v16
	v_lshl_add_u64 v[166:167], v[18:19], 0, s[6:7]
	v_lshlrev_b64 v[20:21], 11, v[20:21]
	v_add_co_u32_e32 v18, vcc, s5, v18
	v_lshlrev_b64 v[16:17], 11, v[16:17]
	s_nop 0
	v_addc_co_u32_e32 v19, vcc, 0, v19, vcc
	v_lshl_add_u64 v[170:171], v[10:11], 0, v[20:21]
	v_lshl_add_u64 v[168:169], v[10:11], 0, v[16:17]
	v_lshlrev_b32_e32 v0, 1, v22
	v_lshrrev_b32_e32 v20, 1, v22
	v_and_b32_e32 v0, 8, v0
	v_and_b32_e32 v20, 4, v20
	v_and_b32_e32 v21, 19, v22
	v_or3_b32 v0, v0, v21, v20
	v_lshlrev_b32_e32 v36, 4, v181
	v_mul_u32_u24_e32 v20, 0x110, v0
	v_add3_u32 v165, 0, v20, v36
	v_ashrrev_i32_e32 v159, 31, v158
	v_add_u32_e32 v163, 0, v36
	s_waitcnt vmcnt(1)
	ds_write_b128 v162, v[2:5]
	s_waitcnt vmcnt(0)
	ds_write_b128 v164, v[12:15]
	s_waitcnt lgkmcnt(0)
	s_barrier
	global_load_dwordx4 v[12:15], v[170:171], off
	global_load_dwordx4 v[2:5], v[18:19], off
	global_load_dwordx4 v[154:157], v[166:167], off offset:32
	global_load_dwordx4 v[150:153], v[166:167], off offset:64
	global_load_dwordx4 v[146:149], v[166:167], off offset:96
	global_load_dwordx4 v[142:145], v[166:167], off offset:128
	global_load_dwordx4 v[138:141], v[166:167], off offset:160
	global_load_dwordx4 v[134:137], v[166:167], off offset:192
	global_load_dwordx4 v[16:19], v[168:169], off
	global_load_dwordx4 v[130:133], v[166:167], off offset:224
	ds_read_b128 v[20:23], v165
	ds_read_b128 v[24:27], v165 offset:32
	ds_read_b128 v[28:31], v165 offset:8704
	ds_read_b128 v[32:35], v165 offset:8736
	s_waitcnt vmcnt(8) lgkmcnt(3)
	v_mfma_f32_32x32x16_bf16 v[114:129], v[20:23], v[2:5], 0
	v_mad_u32_u24 v0, v0, s8, v163
	s_waitcnt lgkmcnt(1)
	v_mfma_f32_32x32x16_bf16 v[82:97], v[28:31], v[2:5], 0
	s_waitcnt vmcnt(7)
	v_mfma_f32_32x32x16_bf16 v[114:129], v[24:27], v[154:157], v[114:129]
	ds_read_b128 v[20:23], v0 offset:64
	ds_read_b128 v[24:27], v0 offset:96
	ds_read_b128 v[28:31], v0 offset:8768
	ds_read_b128 v[36:39], v0 offset:8800
	s_waitcnt lgkmcnt(4)
	v_mfma_f32_32x32x16_bf16 v[82:97], v[32:35], v[154:157], v[82:97]
	s_waitcnt vmcnt(6) lgkmcnt(3)
	v_mfma_f32_32x32x16_bf16 v[114:129], v[20:23], v[150:153], v[114:129]
	s_waitcnt lgkmcnt(1)
	v_mfma_f32_32x32x16_bf16 v[82:97], v[28:31], v[150:153], v[82:97]
	s_waitcnt vmcnt(5)
	v_mfma_f32_32x32x16_bf16 v[114:129], v[24:27], v[146:149], v[114:129]
	ds_read_b128 v[20:23], v0 offset:128
	ds_read_b128 v[24:27], v0 offset:160
	ds_read_b128 v[28:31], v0 offset:8832
	ds_read_b128 v[32:35], v0 offset:8864
	s_waitcnt lgkmcnt(4)
	v_mfma_f32_32x32x16_bf16 v[82:97], v[36:39], v[146:149], v[82:97]
	s_waitcnt vmcnt(4) lgkmcnt(3)
	v_mfma_f32_32x32x16_bf16 v[114:129], v[20:23], v[142:145], v[114:129]
	s_waitcnt lgkmcnt(1)
	v_mfma_f32_32x32x16_bf16 v[82:97], v[28:31], v[142:145], v[82:97]
	s_waitcnt vmcnt(3)
	v_mfma_f32_32x32x16_bf16 v[114:129], v[24:27], v[138:141], v[114:129]
	ds_read_b128 v[20:23], v0 offset:192
	ds_read_b128 v[24:27], v0 offset:224
	ds_read_b128 v[28:31], v0 offset:8896
	ds_read_b128 v[36:39], v0 offset:8928
	s_waitcnt lgkmcnt(4)
	v_mfma_f32_32x32x16_bf16 v[82:97], v[32:35], v[138:141], v[82:97]
	s_waitcnt vmcnt(2) lgkmcnt(3)
	v_mfma_f32_32x32x16_bf16 v[114:129], v[20:23], v[134:137], v[114:129]
	s_waitcnt lgkmcnt(1)
	v_mfma_f32_32x32x16_bf16 v[82:97], v[28:31], v[134:137], v[82:97]
	s_waitcnt vmcnt(0)
	v_mfma_f32_32x32x16_bf16 v[114:129], v[24:27], v[130:133], v[114:129]
	s_waitcnt lgkmcnt(0)
	v_mfma_f32_32x32x16_bf16 v[82:97], v[36:39], v[130:133], v[82:97]
	s_or_b32 s5, s4, 0x80
	ds_write_b128 v162, v[16:19] offset:18432
	ds_write_b128 v164, v[12:15] offset:18432
	v_add_u32_e32 v12, s5, v40
	v_ashrrev_i32_e32 v13, 31, v12
	v_lshlrev_b64 v[12:13], 11, v[12:13]
	v_lshl_add_u64 v[172:173], v[10:11], 0, v[12:13]
	v_add_u32_e32 v12, s5, v41
	v_ashrrev_i32_e32 v13, 31, v12
	v_lshlrev_b64 v[12:13], 11, v[12:13]
	s_waitcnt lgkmcnt(0)
	s_barrier
	v_lshl_add_u64 v[174:175], v[10:11], 0, v[12:13]
	global_load_dwordx4 v[12:15], v[172:173], off
	global_load_dwordx4 v[16:19], v[174:175], off
	ds_read_b128 v[20:23], v165 offset:18432
	ds_read_b128 v[24:27], v165 offset:18464
	ds_read_b128 v[28:31], v165 offset:27136
	ds_read_b128 v[32:35], v165 offset:27168
	s_waitcnt lgkmcnt(3)
	v_mfma_f32_32x32x16_bf16 v[98:113], v[20:23], v[2:5], 0
	s_waitcnt lgkmcnt(1)
	v_mfma_f32_32x32x16_bf16 v[50:65], v[28:31], v[2:5], 0
	v_mfma_f32_32x32x16_bf16 v[98:113], v[24:27], v[154:157], v[98:113]
	ds_read_b128 v[20:23], v0 offset:18496
	ds_read_b128 v[24:27], v0 offset:18528
	ds_read_b128 v[28:31], v0 offset:27200
	ds_read_b128 v[36:39], v0 offset:27232
	s_waitcnt lgkmcnt(4)
	v_mfma_f32_32x32x16_bf16 v[50:65], v[32:35], v[154:157], v[50:65]
	s_waitcnt lgkmcnt(3)
	v_mfma_f32_32x32x16_bf16 v[98:113], v[20:23], v[150:153], v[98:113]
	s_waitcnt lgkmcnt(1)
	v_mfma_f32_32x32x16_bf16 v[50:65], v[28:31], v[150:153], v[50:65]
	v_mfma_f32_32x32x16_bf16 v[98:113], v[24:27], v[146:149], v[98:113]
	ds_read_b128 v[20:23], v0 offset:18560
	ds_read_b128 v[24:27], v0 offset:18592
	ds_read_b128 v[28:31], v0 offset:27264
	ds_read_b128 v[32:35], v0 offset:27296
	s_waitcnt lgkmcnt(4)
	v_mfma_f32_32x32x16_bf16 v[50:65], v[36:39], v[146:149], v[50:65]
	s_waitcnt lgkmcnt(3)
	v_mfma_f32_32x32x16_bf16 v[98:113], v[20:23], v[142:145], v[98:113]
	s_waitcnt lgkmcnt(1)
	v_mfma_f32_32x32x16_bf16 v[50:65], v[28:31], v[142:145], v[50:65]
	v_mfma_f32_32x32x16_bf16 v[98:113], v[24:27], v[138:141], v[98:113]
	ds_read_b128 v[20:23], v0 offset:18624
	ds_read_b128 v[24:27], v0 offset:18656
	ds_read_b128 v[28:31], v0 offset:27328
	ds_read_b128 v[36:39], v0 offset:27360
	s_waitcnt lgkmcnt(4)
	v_mfma_f32_32x32x16_bf16 v[50:65], v[32:35], v[138:141], v[50:65]
	s_waitcnt lgkmcnt(3)
	v_mfma_f32_32x32x16_bf16 v[98:113], v[20:23], v[134:137], v[98:113]
	s_waitcnt lgkmcnt(1)
	v_mfma_f32_32x32x16_bf16 v[50:65], v[28:31], v[134:137], v[50:65]
	v_mfma_f32_32x32x16_bf16 v[98:113], v[24:27], v[130:133], v[98:113]
	s_waitcnt lgkmcnt(0)
	v_mfma_f32_32x32x16_bf16 v[50:65], v[36:39], v[130:133], v[50:65]
	s_or_b32 s4, s4, 0xc0
	s_waitcnt vmcnt(1)
	ds_write_b128 v162, v[12:15]
	s_waitcnt vmcnt(0)
	ds_write_b128 v164, v[16:19]
	v_add_u32_e32 v12, s4, v40
	v_ashrrev_i32_e32 v13, 31, v12
	v_lshlrev_b64 v[12:13], 11, v[12:13]
	v_lshl_add_u64 v[176:177], v[10:11], 0, v[12:13]
	v_add_u32_e32 v12, s4, v41
	v_ashrrev_i32_e32 v13, 31, v12
	v_lshlrev_b64 v[12:13], 11, v[12:13]
	s_waitcnt lgkmcnt(0)
	s_barrier
	v_lshl_add_u64 v[178:179], v[10:11], 0, v[12:13]
	global_load_dwordx4 v[10:13], v[176:177], off
	global_load_dwordx4 v[14:17], v[178:179], off
	ds_read_b128 v[18:21], v165
	ds_read_b128 v[22:25], v165 offset:32
	ds_read_b128 v[26:29], v165 offset:8704
	ds_read_b128 v[30:33], v165 offset:8736
	s_waitcnt lgkmcnt(3)
	v_mfma_f32_32x32x16_bf16 v[66:81], v[18:21], v[2:5], 0
	s_waitcnt lgkmcnt(1)
	v_mfma_f32_32x32x16_bf16 v[34:49], v[26:29], v[2:5], 0
	v_mfma_f32_32x32x16_bf16 v[66:81], v[22:25], v[154:157], v[66:81]
	ds_read_b128 v[18:21], v0 offset:64
	ds_read_b128 v[22:25], v0 offset:96
	ds_read_b128 v[26:29], v0 offset:8768
	ds_read_b128 v[186:189], v0 offset:8800
	s_waitcnt lgkmcnt(4)
	v_mfma_f32_32x32x16_bf16 v[34:49], v[30:33], v[154:157], v[34:49]
	s_waitcnt lgkmcnt(3)
	v_mfma_f32_32x32x16_bf16 v[66:81], v[18:21], v[150:153], v[66:81]
	s_waitcnt lgkmcnt(1)
	v_mfma_f32_32x32x16_bf16 v[34:49], v[26:29], v[150:153], v[34:49]
	v_mfma_f32_32x32x16_bf16 v[66:81], v[22:25], v[146:149], v[66:81]
	ds_read_b128 v[18:21], v0 offset:128
	ds_read_b128 v[22:25], v0 offset:160
	ds_read_b128 v[26:29], v0 offset:8832
	ds_read_b128 v[30:33], v0 offset:8864
	s_waitcnt lgkmcnt(4)
	v_mfma_f32_32x32x16_bf16 v[34:49], v[186:189], v[146:149], v[34:49]
	s_waitcnt lgkmcnt(3)
	v_mfma_f32_32x32x16_bf16 v[66:81], v[18:21], v[142:145], v[66:81]
	s_waitcnt lgkmcnt(1)
	v_mfma_f32_32x32x16_bf16 v[34:49], v[26:29], v[142:145], v[34:49]
	v_mfma_f32_32x32x16_bf16 v[66:81], v[22:25], v[138:141], v[66:81]
	ds_read_b128 v[18:21], v0 offset:192
	ds_read_b128 v[22:25], v0 offset:224
	ds_read_b128 v[26:29], v0 offset:8896
	ds_read_b128 v[186:189], v0 offset:8928
	s_waitcnt lgkmcnt(4)
	v_mfma_f32_32x32x16_bf16 v[34:49], v[30:33], v[138:141], v[34:49]
	s_waitcnt lgkmcnt(3)
	v_mfma_f32_32x32x16_bf16 v[66:81], v[18:21], v[134:137], v[66:81]
	s_waitcnt lgkmcnt(1)
	v_mfma_f32_32x32x16_bf16 v[34:49], v[26:29], v[134:137], v[34:49]
	v_mfma_f32_32x32x16_bf16 v[66:81], v[22:25], v[130:133], v[66:81]
	s_waitcnt lgkmcnt(0)
	v_mfma_f32_32x32x16_bf16 v[34:49], v[186:189], v[130:133], v[34:49]
	s_waitcnt vmcnt(1)
	ds_write_b128 v162, v[10:13] offset:18432
	s_waitcnt vmcnt(0)
	ds_write_b128 v164, v[14:17] offset:18432
	s_waitcnt lgkmcnt(0)
	s_barrier
	global_load_dwordx4 v[186:189], v[6:7], off offset:256
	global_load_dwordx4 v[190:193], v[8:9], off offset:256
	ds_read_b128 v[6:9], v165 offset:18432
	ds_read_b128 v[204:207], v165 offset:18464
	ds_read_b128 v[10:13], v165 offset:27136
	ds_read_b128 v[208:211], v165 offset:27168
	s_waitcnt lgkmcnt(3)
	v_mfma_f32_32x32x16_bf16 v[18:33], v[6:9], v[2:5], 0
	s_waitcnt lgkmcnt(1)
	v_mfma_f32_32x32x16_bf16 v[2:17], v[10:13], v[2:5], 0
	v_mfma_f32_32x32x16_bf16 v[18:33], v[204:207], v[154:157], v[18:33]
	ds_read_b128 v[204:207], v0 offset:18496
	ds_read_b128 v[212:215], v0 offset:18528
	ds_read_b128 v[216:219], v0 offset:27200
	ds_read_b128 v[228:231], v0 offset:27232
	s_waitcnt lgkmcnt(4)
	v_mfma_f32_32x32x16_bf16 v[2:17], v[208:211], v[154:157], v[2:17]
	s_waitcnt lgkmcnt(3)
	v_mfma_f32_32x32x16_bf16 v[18:33], v[204:207], v[150:153], v[18:33]
	s_waitcnt lgkmcnt(1)
	v_mfma_f32_32x32x16_bf16 v[2:17], v[216:219], v[150:153], v[2:17]
	ds_read_b128 v[150:153], v0 offset:18560
	ds_read_b128 v[154:157], v0 offset:18592
	ds_read_b128 v[204:207], v0 offset:27264
	ds_read_b128 v[208:211], v0 offset:27296
	v_mfma_f32_32x32x16_bf16 v[18:33], v[212:215], v[146:149], v[18:33]
	s_waitcnt lgkmcnt(4)
	v_mfma_f32_32x32x16_bf16 v[2:17], v[228:231], v[146:149], v[2:17]
	s_waitcnt lgkmcnt(3)
	v_mfma_f32_32x32x16_bf16 v[18:33], v[150:153], v[142:145], v[18:33]
	s_waitcnt lgkmcnt(1)
	v_mfma_f32_32x32x16_bf16 v[2:17], v[204:207], v[142:145], v[2:17]
	v_mfma_f32_32x32x16_bf16 v[18:33], v[154:157], v[138:141], v[18:33]
	ds_read_b128 v[142:145], v0 offset:18624
	ds_read_b128 v[146:149], v0 offset:18656
	ds_read_b128 v[150:153], v0 offset:27328
	ds_read_b128 v[154:157], v0 offset:27360
	s_waitcnt lgkmcnt(4)
	v_mfma_f32_32x32x16_bf16 v[2:17], v[208:211], v[138:141], v[2:17]
	s_waitcnt lgkmcnt(3)
	v_mfma_f32_32x32x16_bf16 v[18:33], v[142:145], v[134:137], v[18:33]
	s_waitcnt lgkmcnt(1)
	v_mfma_f32_32x32x16_bf16 v[2:17], v[150:153], v[134:137], v[2:17]
	v_mfma_f32_32x32x16_bf16 v[18:33], v[146:149], v[130:133], v[18:33]
	s_waitcnt lgkmcnt(0)
	v_mfma_f32_32x32x16_bf16 v[2:17], v[154:157], v[130:133], v[2:17]
	s_waitcnt vmcnt(1)
	ds_write_b128 v162, v[186:189]
	s_waitcnt vmcnt(0)
	ds_write_b128 v164, v[190:193]
	s_waitcnt lgkmcnt(0)
	s_barrier
	global_load_dwordx4 v[154:157], v[168:169], off offset:256
	s_nop 0
	global_load_dwordx4 v[168:171], v[170:171], off offset:256
	s_nop 0
	global_load_dwordx4 v[186:189], v[166:167], off offset:256
	global_load_dwordx4 v[190:193], v[166:167], off offset:288
	global_load_dwordx4 v[150:153], v[166:167], off offset:320
	global_load_dwordx4 v[146:149], v[166:167], off offset:352
	global_load_dwordx4 v[142:145], v[166:167], off offset:384
	global_load_dwordx4 v[138:141], v[166:167], off offset:416
	global_load_dwordx4 v[134:137], v[166:167], off offset:448
	global_load_dwordx4 v[130:133], v[166:167], off offset:480
	ds_read_b128 v[204:207], v165
	ds_read_b128 v[208:211], v165 offset:32
	ds_read_b128 v[212:215], v165 offset:8704
	ds_read_b128 v[216:219], v165 offset:8736
	s_waitcnt vmcnt(7) lgkmcnt(3)
	v_mfma_f32_32x32x16_bf16 v[114:129], v[204:207], v[186:189], v[114:129]
	s_waitcnt lgkmcnt(1)
	v_mfma_f32_32x32x16_bf16 v[82:97], v[212:215], v[186:189], v[82:97]
	s_waitcnt vmcnt(6)
	v_mfma_f32_32x32x16_bf16 v[114:129], v[208:211], v[190:193], v[114:129]
	ds_read_b128 v[204:207], v0 offset:64
	ds_read_b128 v[208:211], v0 offset:96
	ds_read_b128 v[212:215], v0 offset:8768
	ds_read_b128 v[228:231], v0 offset:8800
	s_waitcnt lgkmcnt(4)
	v_mfma_f32_32x32x16_bf16 v[82:97], v[216:219], v[190:193], v[82:97]
	s_waitcnt vmcnt(5) lgkmcnt(3)
	v_mfma_f32_32x32x16_bf16 v[114:129], v[204:207], v[150:153], v[114:129]
	s_waitcnt lgkmcnt(1)
	v_mfma_f32_32x32x16_bf16 v[82:97], v[212:215], v[150:153], v[82:97]
	s_waitcnt vmcnt(4)
	v_mfma_f32_32x32x16_bf16 v[114:129], v[208:211], v[146:149], v[114:129]
	ds_read_b128 v[204:207], v0 offset:128
	ds_read_b128 v[208:211], v0 offset:160
	ds_read_b128 v[212:215], v0 offset:8832
	ds_read_b128 v[216:219], v0 offset:8864
	s_waitcnt lgkmcnt(4)
	v_mfma_f32_32x32x16_bf16 v[82:97], v[228:231], v[146:149], v[82:97]
	s_waitcnt vmcnt(3) lgkmcnt(3)
	v_mfma_f32_32x32x16_bf16 v[114:129], v[204:207], v[142:145], v[114:129]
	s_waitcnt lgkmcnt(1)
	v_mfma_f32_32x32x16_bf16 v[82:97], v[212:215], v[142:145], v[82:97]
	s_waitcnt vmcnt(2)
	v_mfma_f32_32x32x16_bf16 v[114:129], v[208:211], v[138:141], v[114:129]
	ds_read_b128 v[204:207], v0 offset:192
	ds_read_b128 v[208:211], v0 offset:224
	ds_read_b128 v[212:215], v0 offset:8896
	ds_read_b128 v[228:231], v0 offset:8928
	s_waitcnt lgkmcnt(4)
	v_mfma_f32_32x32x16_bf16 v[82:97], v[216:219], v[138:141], v[82:97]
	s_waitcnt vmcnt(1) lgkmcnt(3)
	v_mfma_f32_32x32x16_bf16 v[114:129], v[204:207], v[134:137], v[114:129]
	s_waitcnt lgkmcnt(1)
	v_mfma_f32_32x32x16_bf16 v[82:97], v[212:215], v[134:137], v[82:97]
	s_waitcnt vmcnt(0)
	v_mfma_f32_32x32x16_bf16 v[114:129], v[208:211], v[130:133], v[114:129]
	s_waitcnt lgkmcnt(0)
	v_mfma_f32_32x32x16_bf16 v[82:97], v[228:231], v[130:133], v[82:97]
	ds_write_b128 v162, v[154:157] offset:18432
	ds_write_b128 v164, v[168:171] offset:18432
	s_waitcnt lgkmcnt(0)
	s_barrier
	global_load_dwordx4 v[154:157], v[172:173], off offset:256
	global_load_dwordx4 v[166:169], v[174:175], off offset:256
	ds_read_b128 v[170:173], v165 offset:18432
	ds_read_b128 v[204:207], v165 offset:18464
	ds_read_b128 v[208:211], v165 offset:27136
	ds_read_b128 v[212:215], v165 offset:27168
	s_waitcnt lgkmcnt(3)
	v_mfma_f32_32x32x16_bf16 v[98:113], v[170:173], v[186:189], v[98:113]
	s_waitcnt lgkmcnt(1)
	v_mfma_f32_32x32x16_bf16 v[50:65], v[208:211], v[186:189], v[50:65]
	v_mfma_f32_32x32x16_bf16 v[98:113], v[204:207], v[190:193], v[98:113]
	ds_read_b128 v[170:173], v0 offset:18496
	ds_read_b128 v[204:207], v0 offset:18528
	ds_read_b128 v[208:211], v0 offset:27200
	ds_read_b128 v[216:219], v0 offset:27232
	s_waitcnt lgkmcnt(4)
	v_mfma_f32_32x32x16_bf16 v[50:65], v[212:215], v[190:193], v[50:65]
	s_waitcnt lgkmcnt(3)
	v_mfma_f32_32x32x16_bf16 v[98:113], v[170:173], v[150:153], v[98:113]
	s_waitcnt lgkmcnt(1)
	v_mfma_f32_32x32x16_bf16 v[50:65], v[208:211], v[150:153], v[50:65]
	v_mfma_f32_32x32x16_bf16 v[98:113], v[204:207], v[146:149], v[98:113]
	ds_read_b128 v[170:173], v0 offset:18560
	ds_read_b128 v[204:207], v0 offset:18592
	ds_read_b128 v[208:211], v0 offset:27264
	ds_read_b128 v[212:215], v0 offset:27296
	s_waitcnt lgkmcnt(4)
	v_mfma_f32_32x32x16_bf16 v[50:65], v[216:219], v[146:149], v[50:65]
	s_waitcnt lgkmcnt(3)
	v_mfma_f32_32x32x16_bf16 v[98:113], v[170:173], v[142:145], v[98:113]
	s_waitcnt lgkmcnt(1)
	v_mfma_f32_32x32x16_bf16 v[50:65], v[208:211], v[142:145], v[50:65]
	v_mfma_f32_32x32x16_bf16 v[98:113], v[204:207], v[138:141], v[98:113]
	ds_read_b128 v[170:173], v0 offset:18624
	ds_read_b128 v[204:207], v0 offset:18656
	ds_read_b128 v[208:211], v0 offset:27328
	ds_read_b128 v[216:219], v0 offset:27360
	s_waitcnt lgkmcnt(4)
	v_mfma_f32_32x32x16_bf16 v[50:65], v[212:215], v[138:141], v[50:65]
	s_waitcnt lgkmcnt(3)
	v_mfma_f32_32x32x16_bf16 v[98:113], v[170:173], v[134:137], v[98:113]
	s_waitcnt lgkmcnt(1)
	v_mfma_f32_32x32x16_bf16 v[50:65], v[208:211], v[134:137], v[50:65]
	v_mfma_f32_32x32x16_bf16 v[98:113], v[204:207], v[130:133], v[98:113]
	s_waitcnt lgkmcnt(0)
	v_mfma_f32_32x32x16_bf16 v[50:65], v[216:219], v[130:133], v[50:65]
	s_waitcnt vmcnt(1)
	ds_write_b128 v162, v[154:157]
	s_waitcnt vmcnt(0)
	ds_write_b128 v164, v[166:169]
	s_waitcnt lgkmcnt(0)
	s_barrier
	global_load_dwordx4 v[154:157], v[176:177], off offset:256
	global_load_dwordx4 v[166:169], v[178:179], off offset:256
	ds_read_b128 v[170:173], v165
	ds_read_b128 v[174:177], v165 offset:32
	ds_read_b128 v[204:207], v165 offset:8704
	ds_read_b128 v[208:211], v165 offset:8736
	s_waitcnt lgkmcnt(3)
	v_mfma_f32_32x32x16_bf16 v[66:81], v[170:173], v[186:189], v[66:81]
	s_waitcnt lgkmcnt(1)
	v_mfma_f32_32x32x16_bf16 v[34:49], v[204:207], v[186:189], v[34:49]
	v_mfma_f32_32x32x16_bf16 v[66:81], v[174:177], v[190:193], v[66:81]
	ds_read_b128 v[170:173], v0 offset:64
	ds_read_b128 v[174:177], v0 offset:96
	ds_read_b128 v[204:207], v0 offset:8768
	ds_read_b128 v[212:215], v0 offset:8800
	s_waitcnt lgkmcnt(4)
	v_mfma_f32_32x32x16_bf16 v[34:49], v[208:211], v[190:193], v[34:49]
	s_waitcnt lgkmcnt(3)
	v_mfma_f32_32x32x16_bf16 v[66:81], v[170:173], v[150:153], v[66:81]
	s_waitcnt lgkmcnt(1)
	v_mfma_f32_32x32x16_bf16 v[34:49], v[204:207], v[150:153], v[34:49]
	v_mfma_f32_32x32x16_bf16 v[66:81], v[174:177], v[146:149], v[66:81]
	ds_read_b128 v[170:173], v0 offset:128
	ds_read_b128 v[174:177], v0 offset:160
	ds_read_b128 v[204:207], v0 offset:8832
	ds_read_b128 v[208:211], v0 offset:8864
	s_waitcnt lgkmcnt(4)
	v_mfma_f32_32x32x16_bf16 v[34:49], v[212:215], v[146:149], v[34:49]
	s_waitcnt lgkmcnt(3)
	v_mfma_f32_32x32x16_bf16 v[66:81], v[170:173], v[142:145], v[66:81]
	s_waitcnt lgkmcnt(1)
	v_mfma_f32_32x32x16_bf16 v[34:49], v[204:207], v[142:145], v[34:49]
	v_mfma_f32_32x32x16_bf16 v[66:81], v[174:177], v[138:141], v[66:81]
	ds_read_b128 v[170:173], v0 offset:192
	ds_read_b128 v[174:177], v0 offset:224
	ds_read_b128 v[204:207], v0 offset:8896
	ds_read_b128 v[212:215], v0 offset:8928
	s_waitcnt lgkmcnt(4)
	v_mfma_f32_32x32x16_bf16 v[34:49], v[208:211], v[138:141], v[34:49]
	s_waitcnt lgkmcnt(3)
	v_mfma_f32_32x32x16_bf16 v[66:81], v[170:173], v[134:137], v[66:81]
	s_waitcnt lgkmcnt(1)
	v_mfma_f32_32x32x16_bf16 v[34:49], v[204:207], v[134:137], v[34:49]
	v_mfma_f32_32x32x16_bf16 v[66:81], v[174:177], v[130:133], v[66:81]
	s_waitcnt lgkmcnt(0)
	v_mfma_f32_32x32x16_bf16 v[34:49], v[212:215], v[130:133], v[34:49]
	s_waitcnt vmcnt(1)
	ds_write_b128 v162, v[154:157] offset:18432
	s_waitcnt vmcnt(0)
	ds_write_b128 v164, v[166:169] offset:18432
	s_waitcnt lgkmcnt(0)
	s_barrier
	ds_read_b128 v[154:157], v165 offset:18432
	ds_read_b128 v[166:169], v165 offset:18464
	ds_read_b128 v[170:173], v165 offset:27136
	ds_read_b128 v[174:177], v165 offset:27168
	s_waitcnt lgkmcnt(3)
	v_mfma_f32_32x32x16_bf16 v[18:33], v[154:157], v[186:189], v[18:33]
	s_waitcnt lgkmcnt(1)
	v_mfma_f32_32x32x16_bf16 v[2:17], v[170:173], v[186:189], v[2:17]
	v_mfma_f32_32x32x16_bf16 v[18:33], v[166:169], v[190:193], v[18:33]
	ds_read_b128 v[154:157], v0 offset:18496
	ds_read_b128 v[164:167], v0 offset:18528
	ds_read_b128 v[168:171], v0 offset:27200
	ds_read_b128 v[186:189], v0 offset:27232
	s_waitcnt lgkmcnt(4)
	v_mfma_f32_32x32x16_bf16 v[2:17], v[174:177], v[190:193], v[2:17]
	s_waitcnt lgkmcnt(3)
	v_mfma_f32_32x32x16_bf16 v[18:33], v[154:157], v[150:153], v[18:33]
	s_waitcnt lgkmcnt(1)
	v_mfma_f32_32x32x16_bf16 v[2:17], v[168:171], v[150:153], v[2:17]
	v_mfma_f32_32x32x16_bf16 v[18:33], v[164:167], v[146:149], v[18:33]
	ds_read_b128 v[150:153], v0 offset:18560
	ds_read_b128 v[154:157], v0 offset:18592
	ds_read_b128 v[164:167], v0 offset:27264
	ds_read_b128 v[168:171], v0 offset:27296
	s_waitcnt lgkmcnt(4)
	v_mfma_f32_32x32x16_bf16 v[2:17], v[186:189], v[146:149], v[2:17]
	s_waitcnt lgkmcnt(3)
	v_mfma_f32_32x32x16_bf16 v[18:33], v[150:153], v[142:145], v[18:33]
	s_waitcnt lgkmcnt(1)
	v_mfma_f32_32x32x16_bf16 v[2:17], v[164:167], v[142:145], v[2:17]
	v_mfma_f32_32x32x16_bf16 v[18:33], v[154:157], v[138:141], v[18:33]
	ds_read_b128 v[142:145], v0 offset:18624
	ds_read_b128 v[146:149], v0 offset:18656
	ds_read_b128 v[150:153], v0 offset:27328
	ds_read_b128 v[154:157], v0 offset:27360
	s_waitcnt lgkmcnt(4)
	v_mfma_f32_32x32x16_bf16 v[2:17], v[168:171], v[138:141], v[2:17]
	s_waitcnt lgkmcnt(3)
	v_mfma_f32_32x32x16_bf16 v[18:33], v[142:145], v[134:137], v[18:33]
	s_waitcnt lgkmcnt(1)
	v_mfma_f32_32x32x16_bf16 v[2:17], v[150:153], v[134:137], v[2:17]
	v_mfma_f32_32x32x16_bf16 v[18:33], v[146:149], v[130:133], v[18:33]
	s_waitcnt lgkmcnt(0)
	v_mfma_f32_32x32x16_bf16 v[2:17], v[154:157], v[130:133], v[2:17]
	v_max3_f32 v0, v114, s33, v115
	v_max3_f32 v0, v0, v116, v117
	v_max3_f32 v0, v0, v118, v119
	v_max3_f32 v0, v0, v120, v121
	v_max3_f32 v0, v0, v122, v123
	v_max3_f32 v0, v0, v124, v125
	v_max3_f32 v0, v0, v126, v127
	v_max3_f32 v0, v0, v128, v129
	v_max3_f32 v0, v0, v82, v83
	v_max3_f32 v0, v0, v84, v85
	v_max3_f32 v0, v0, v86, v87
	v_max3_f32 v0, v0, v88, v89
	v_max3_f32 v0, v0, v90, v91
	v_max3_f32 v0, v0, v92, v93
	v_max3_f32 v0, v0, v94, v95
	v_max3_f32 v0, v0, v96, v97
	v_max3_f32 v0, v0, v98, v99
	v_max3_f32 v0, v0, v100, v101
	v_max3_f32 v0, v0, v102, v103
	v_max3_f32 v0, v0, v104, v105
	v_max3_f32 v0, v0, v106, v107
	v_max3_f32 v0, v0, v108, v109
	v_max3_f32 v0, v0, v110, v111
	v_max3_f32 v0, v0, v112, v113
	v_max3_f32 v0, v0, v50, v51
	v_max3_f32 v0, v0, v52, v53
	v_max3_f32 v0, v0, v54, v55
	v_max3_f32 v0, v0, v56, v57
	v_max3_f32 v0, v0, v58, v59
	v_max3_f32 v0, v0, v60, v61
	v_max3_f32 v0, v0, v62, v63
	v_max3_f32 v0, v0, v64, v65
	v_max3_f32 v0, v0, v66, v67
	v_max3_f32 v0, v0, v68, v69
	v_max3_f32 v0, v0, v70, v71
	v_max3_f32 v0, v0, v72, v73
	v_max3_f32 v0, v0, v74, v75
	v_max3_f32 v0, v0, v76, v77
	v_max3_f32 v0, v0, v78, v79
	v_max3_f32 v0, v0, v80, v81
	v_max3_f32 v0, v0, v34, v35
	v_max3_f32 v0, v0, v36, v37
	v_max3_f32 v0, v0, v38, v39
	v_max3_f32 v0, v0, v40, v41
	v_max3_f32 v0, v0, v42, v43
	v_max3_f32 v0, v0, v44, v45
	v_max3_f32 v0, v0, v46, v47
	v_max3_f32 v0, v0, v48, v49
	v_max3_f32 v0, v0, v18, v19
	v_max3_f32 v0, v0, v20, v21
	v_max3_f32 v0, v0, v22, v23
	v_max3_f32 v0, v0, v24, v25
	v_max3_f32 v0, v0, v26, v27
	v_max3_f32 v0, v0, v28, v29
	v_max3_f32 v0, v0, v30, v31
	v_max3_f32 v0, v0, v32, v33
	v_max3_f32 v0, v0, v2, v3
	v_max3_f32 v0, v0, v4, v5
	v_max3_f32 v0, v0, v6, v7
	v_max3_f32 v0, v0, v8, v9
	v_max3_f32 v0, v0, v10, v11
	v_max3_f32 v0, v0, v12, v13
	v_max3_f32 v0, v0, v14, v15
	v_max3_f32 v0, v0, v16, v17
	v_mov_b32_e32 v130, v0
	v_mov_b32_e32 v131, v0
	s_nop 1
	v_permlane32_swap_b32_e32 v130, v131
	v_cmp_eq_u32_e32 vcc, v130, v0
	s_lshl_b32 s1, s1, 9
	v_readlane_b32 s4, v255, 43
	v_cndmask_b32_e32 v130, v130, v131, vcc
	v_max_f32_e32 v130, v130, v130
	v_max_f32_e32 v131, v0, v130
	v_mov_b32_e32 v130, v17
	v_pk_mul_f32 v[130:131], v[130:131], s[76:77] op_sel_hi:[1,0]
	v_ashrrev_i32_e32 v166, 3, v182
	v_fma_f32 v0, v114, s76, -v131
	v_exp_f32_e32 v0, v0
	v_fma_f32 v17, v115, s76, -v131
	v_exp_f32_e32 v17, v17
	v_fma_f32 v114, v116, s76, -v131
	v_exp_f32_e32 v115, v114
	v_fma_f32 v114, v117, s76, -v131
	v_exp_f32_e32 v116, v114
	v_fma_f32 v117, v118, s76, -v131
	v_add_f32_e32 v114, 0, v0
	v_exp_f32_e32 v117, v117
	v_fma_f32 v118, v119, s76, -v131
	v_add_f32_e32 v114, v17, v114
	v_exp_f32_e32 v118, v118
	v_fma_f32 v119, v120, s76, -v131
	v_add_f32_e32 v114, v115, v114
	v_exp_f32_e32 v119, v119
	v_fma_f32 v120, v121, s76, -v131
	v_add_f32_e32 v114, v116, v114
	v_exp_f32_e32 v120, v120
	v_add_f32_e32 v114, v117, v114
	v_add_f32_e32 v114, v118, v114
	v_add_f32_e32 v114, v119, v114
	v_add_f32_e32 v121, v120, v114
	v_cvt_pk_bf16_f32 v114, v0, v17
	v_fma_f32 v0, v122, s76, -v131
	v_exp_f32_e32 v0, v0
	v_fma_f32 v17, v123, s76, -v131
	v_cvt_pk_bf16_f32 v115, v115, v116
	v_cvt_pk_bf16_f32 v116, v117, v118
	v_exp_f32_e32 v17, v17
	v_fma_f32 v118, v124, s76, -v131
	v_cvt_pk_bf16_f32 v117, v119, v120
	v_exp_f32_e32 v119, v118
	v_fma_f32 v118, v125, s76, -v131
	v_exp_f32_e32 v120, v118
	v_add_f32_e32 v118, v0, v121
	v_fma_f32 v121, v126, s76, -v131
	v_exp_f32_e32 v121, v121
	v_fma_f32 v122, v127, s76, -v131
	v_add_f32_e32 v118, v17, v118
	v_exp_f32_e32 v122, v122
	v_fma_f32 v123, v128, s76, -v131
	v_add_f32_e32 v118, v119, v118
	v_exp_f32_e32 v123, v123
	v_fma_f32 v124, v129, s76, -v131
	v_add_f32_e32 v118, v120, v118
	v_exp_f32_e32 v124, v124
	v_add_f32_e32 v118, v121, v118
	v_add_f32_e32 v118, v122, v118
	v_add_f32_e32 v118, v123, v118
	v_add_f32_e32 v125, v124, v118
	v_cvt_pk_bf16_f32 v118, v0, v17
	v_fma_f32 v0, v82, s76, -v131
	v_exp_f32_e32 v0, v0
	v_fma_f32 v17, v83, s76, -v131
	v_exp_f32_e32 v17, v17
	v_fma_f32 v82, v84, s76, -v131
	v_exp_f32_e32 v83, v82
	v_fma_f32 v82, v85, s76, -v131
	v_exp_f32_e32 v84, v82
	v_fma_f32 v85, v86, s76, -v131
	v_add_f32_e32 v82, v0, v125
	v_exp_f32_e32 v85, v85
	v_fma_f32 v86, v87, s76, -v131
	v_add_f32_e32 v82, v17, v82
	v_exp_f32_e32 v86, v86
	v_fma_f32 v87, v88, s76, -v131
	v_add_f32_e32 v82, v83, v82
	v_exp_f32_e32 v87, v87
	v_fma_f32 v88, v89, s76, -v131
	v_add_f32_e32 v82, v84, v82
	v_exp_f32_e32 v88, v88
	v_add_f32_e32 v82, v85, v82
	v_add_f32_e32 v82, v86, v82
	v_add_f32_e32 v82, v87, v82
	v_add_f32_e32 v89, v88, v82
	v_cvt_pk_bf16_f32 v82, v0, v17
	v_fma_f32 v0, v90, s76, -v131
	v_exp_f32_e32 v0, v0
	v_fma_f32 v17, v91, s76, -v131
	v_cvt_pk_bf16_f32 v83, v83, v84
	v_cvt_pk_bf16_f32 v84, v85, v86
	v_exp_f32_e32 v17, v17
	v_fma_f32 v86, v92, s76, -v131
	v_cvt_pk_bf16_f32 v85, v87, v88
	v_exp_f32_e32 v87, v86
	v_fma_f32 v86, v93, s76, -v131
	v_exp_f32_e32 v88, v86
	v_add_f32_e32 v86, v0, v89
	v_fma_f32 v89, v94, s76, -v131
	v_exp_f32_e32 v89, v89
	v_fma_f32 v90, v95, s76, -v131
	v_add_f32_e32 v86, v17, v86
	v_exp_f32_e32 v90, v90
	v_fma_f32 v91, v96, s76, -v131
	v_add_f32_e32 v86, v87, v86
	v_exp_f32_e32 v91, v91
	v_fma_f32 v92, v97, s76, -v131
	v_add_f32_e32 v86, v88, v86
	v_exp_f32_e32 v92, v92
	v_add_f32_e32 v86, v89, v86
	v_add_f32_e32 v86, v90, v86
	v_add_f32_e32 v86, v91, v86
	v_add_f32_e32 v93, v92, v86
	v_cvt_pk_bf16_f32 v86, v0, v17
	v_fma_f32 v0, v98, s76, -v131
	v_exp_f32_e32 v0, v0
	v_fma_f32 v17, v99, s76, -v131
	v_cvt_pk_bf16_f32 v87, v87, v88
	v_cvt_pk_bf16_f32 v88, v89, v90
	v_exp_f32_e32 v17, v17
	v_fma_f32 v90, v100, s76, -v131
	v_cvt_pk_bf16_f32 v89, v91, v92
	v_exp_f32_e32 v91, v90
	v_fma_f32 v90, v101, s76, -v131
	v_exp_f32_e32 v92, v90
	v_add_f32_e32 v90, v0, v93
	v_fma_f32 v93, v102, s76, -v131
	v_exp_f32_e32 v93, v93
	v_fma_f32 v94, v103, s76, -v131
	v_add_f32_e32 v90, v17, v90
	v_exp_f32_e32 v94, v94
	v_fma_f32 v95, v104, s76, -v131
	v_add_f32_e32 v90, v91, v90
	v_exp_f32_e32 v95, v95
	v_fma_f32 v96, v105, s76, -v131
	v_add_f32_e32 v90, v92, v90
	v_exp_f32_e32 v96, v96
	v_add_f32_e32 v90, v93, v90
	v_add_f32_e32 v90, v94, v90
	v_add_f32_e32 v90, v95, v90
	v_add_f32_e32 v97, v96, v90
	v_cvt_pk_bf16_f32 v90, v0, v17
	v_fma_f32 v0, v106, s76, -v131
	v_exp_f32_e32 v0, v0
	v_fma_f32 v17, v107, s76, -v131
	v_cvt_pk_bf16_f32 v91, v91, v92
	v_cvt_pk_bf16_f32 v92, v93, v94
	v_exp_f32_e32 v17, v17
	v_fma_f32 v94, v108, s76, -v131
	v_cvt_pk_bf16_f32 v93, v95, v96
	v_exp_f32_e32 v95, v94
	v_fma_f32 v94, v109, s76, -v131
	v_exp_f32_e32 v96, v94
	v_add_f32_e32 v94, v0, v97
	v_fma_f32 v97, v110, s76, -v131
	v_exp_f32_e32 v97, v97
	v_fma_f32 v98, v111, s76, -v131
	v_add_f32_e32 v94, v17, v94
	v_exp_f32_e32 v98, v98
	v_fma_f32 v99, v112, s76, -v131
	v_add_f32_e32 v94, v95, v94
	v_exp_f32_e32 v99, v99
	v_fma_f32 v100, v113, s76, -v131
	v_add_f32_e32 v94, v96, v94
	v_exp_f32_e32 v100, v100
	v_add_f32_e32 v94, v97, v94
	v_add_f32_e32 v94, v98, v94
	v_add_f32_e32 v94, v99, v94
	v_add_f32_e32 v101, v100, v94
	v_cvt_pk_bf16_f32 v94, v0, v17
	v_fma_f32 v0, v50, s76, -v131
	v_exp_f32_e32 v0, v0
	v_fma_f32 v17, v51, s76, -v131
	v_exp_f32_e32 v17, v17
	v_fma_f32 v50, v52, s76, -v131
	v_exp_f32_e32 v50, v50
	v_fma_f32 v51, v53, s76, -v131
	v_exp_f32_e32 v51, v51
	v_fma_f32 v53, v54, s76, -v131
	v_add_f32_e32 v52, v0, v101
	v_exp_f32_e32 v53, v53
	v_fma_f32 v54, v55, s76, -v131
	v_add_f32_e32 v52, v17, v52
	v_exp_f32_e32 v54, v54
	v_fma_f32 v55, v56, s76, -v131
	v_add_f32_e32 v52, v50, v52
	v_exp_f32_e32 v55, v55
	v_fma_f32 v56, v57, s76, -v131
	v_cvt_pk_bf16_f32 v95, v95, v96
	v_cvt_pk_bf16_f32 v96, v97, v98
	v_add_f32_e32 v52, v51, v52
	v_exp_f32_e32 v56, v56
	v_cvt_pk_bf16_f32 v98, v0, v17
	v_fma_f32 v0, v58, s76, -v131
	v_add_f32_e32 v52, v53, v52
	v_exp_f32_e32 v0, v0
	v_fma_f32 v17, v59, s76, -v131
	v_cvt_pk_bf16_f32 v97, v99, v100
	v_add_f32_e32 v52, v54, v52
	v_cvt_pk_bf16_f32 v99, v50, v51
	v_exp_f32_e32 v17, v17
	v_fma_f32 v50, v60, s76, -v131
	v_add_f32_e32 v52, v55, v52
	v_exp_f32_e32 v50, v50
	v_fma_f32 v51, v61, s76, -v131
	v_add_f32_e32 v52, v56, v52
	v_cvt_pk_bf16_f32 v100, v53, v54
	v_exp_f32_e32 v51, v51
	v_fma_f32 v53, v62, s76, -v131
	v_add_f32_e32 v52, v0, v52
	v_exp_f32_e32 v53, v53
	v_fma_f32 v54, v63, s76, -v131
	v_cvt_pk_bf16_f32 v101, v55, v56
	v_add_f32_e32 v52, v17, v52
	v_exp_f32_e32 v54, v54
	v_fma_f32 v55, v64, s76, -v131
	v_add_f32_e32 v52, v50, v52
	v_exp_f32_e32 v55, v55
	v_fma_f32 v56, v65, s76, -v131
	v_add_f32_e32 v52, v51, v52
	v_exp_f32_e32 v56, v56
	v_cvt_pk_bf16_f32 v102, v0, v17
	v_fma_f32 v0, v66, s76, -v131
	v_add_f32_e32 v52, v53, v52
	v_exp_f32_e32 v0, v0
	v_fma_f32 v17, v67, s76, -v131
	v_add_f32_e32 v52, v54, v52
	v_cvt_pk_bf16_f32 v103, v50, v51
	v_exp_f32_e32 v17, v17
	v_fma_f32 v50, v68, s76, -v131
	v_add_f32_e32 v52, v55, v52
	v_exp_f32_e32 v50, v50
	v_fma_f32 v51, v69, s76, -v131
	v_add_f32_e32 v52, v56, v52
	v_cvt_pk_bf16_f32 v104, v53, v54
	v_exp_f32_e32 v51, v51
	v_fma_f32 v53, v70, s76, -v131
	v_add_f32_e32 v52, v0, v52
	v_exp_f32_e32 v53, v53
	v_fma_f32 v54, v71, s76, -v131
	v_cvt_pk_bf16_f32 v105, v55, v56
	v_add_f32_e32 v52, v17, v52
	v_exp_f32_e32 v54, v54
	v_fma_f32 v55, v72, s76, -v131
	v_add_f32_e32 v52, v50, v52
	v_exp_f32_e32 v55, v55
	v_fma_f32 v56, v73, s76, -v131
	v_add_f32_e32 v52, v51, v52
	v_exp_f32_e32 v56, v56
	v_cvt_pk_bf16_f32 v66, v0, v17
	v_fma_f32 v0, v74, s76, -v131
	v_add_f32_e32 v52, v53, v52
	v_exp_f32_e32 v0, v0
	v_fma_f32 v17, v75, s76, -v131
	v_add_f32_e32 v52, v54, v52
	v_cvt_pk_bf16_f32 v67, v50, v51
	v_exp_f32_e32 v17, v17
	v_fma_f32 v50, v76, s76, -v131
	v_add_f32_e32 v52, v55, v52
	v_exp_f32_e32 v50, v50
	v_fma_f32 v51, v77, s76, -v131
	v_add_f32_e32 v52, v56, v52
	v_cvt_pk_bf16_f32 v68, v53, v54
	v_exp_f32_e32 v51, v51
	v_fma_f32 v53, v78, s76, -v131
	v_add_f32_e32 v52, v0, v52
	v_exp_f32_e32 v53, v53
	v_fma_f32 v54, v79, s76, -v131
	v_cvt_pk_bf16_f32 v69, v55, v56
	v_add_f32_e32 v52, v17, v52
	v_exp_f32_e32 v54, v54
	v_fma_f32 v55, v80, s76, -v131
	v_add_f32_e32 v52, v50, v52
	v_exp_f32_e32 v55, v55
	v_fma_f32 v56, v81, s76, -v131
	v_add_f32_e32 v52, v51, v52
	v_exp_f32_e32 v56, v56
	v_cvt_pk_bf16_f32 v70, v0, v17
	v_fma_f32 v0, v34, s76, -v131
	v_add_f32_e32 v52, v53, v52
	v_exp_f32_e32 v0, v0
	v_fma_f32 v17, v35, s76, -v131
	v_add_f32_e32 v52, v54, v52
	v_exp_f32_e32 v17, v17
	v_fma_f32 v34, v36, s76, -v131
	v_add_f32_e32 v52, v55, v52
	v_exp_f32_e32 v34, v34
	v_fma_f32 v35, v37, s76, -v131
	v_add_f32_e32 v52, v56, v52
	v_exp_f32_e32 v35, v35
	v_fma_f32 v37, v38, s76, -v131
	v_add_f32_e32 v36, v0, v52
	v_exp_f32_e32 v37, v37
	v_fma_f32 v38, v39, s76, -v131
	v_add_f32_e32 v36, v17, v36
	v_exp_f32_e32 v38, v38
	v_fma_f32 v39, v40, s76, -v131
	v_add_f32_e32 v36, v34, v36
	v_exp_f32_e32 v39, v39
	v_fma_f32 v40, v41, s76, -v131
	v_add_f32_e32 v36, v35, v36
	v_exp_f32_e32 v40, v40
	v_cvt_pk_bf16_f32 v74, v0, v17
	v_fma_f32 v0, v42, s76, -v131
	v_add_f32_e32 v36, v37, v36
	v_exp_f32_e32 v17, v0
	v_cvt_pk_bf16_f32 v75, v34, v35
	v_fma_f32 v34, v43, s76, -v131
	v_add_f32_e32 v36, v38, v36
	v_exp_f32_e32 v42, v34
	v_fma_f32 v34, v44, s76, -v131
	v_add_f32_e32 v36, v39, v36
	v_exp_f32_e32 v43, v34
	v_fma_f32 v34, v45, s76, -v131
	v_add_f32_e32 v36, v40, v36
	v_exp_f32_e32 v44, v34
	v_fma_f32 v34, v46, s76, -v131
	v_add_f32_e32 v0, v17, v36
	v_exp_f32_e32 v45, v34
	v_add_f32_e32 v0, v42, v0
	v_add_f32_e32 v0, v43, v0
	v_add_f32_e32 v0, v44, v0
	v_add_f32_e32 v46, v45, v0
	v_fma_f32 v0, v47, s76, -v131
	v_exp_f32_e32 v47, v0
	v_fma_f32 v0, v48, s76, -v131
	v_ashrrev_i32_e32 v167, 3, v184
	v_cvt_pk_bf16_f32 v76, v37, v38
	v_exp_f32_e32 v48, v0
	v_fma_f32 v0, v49, s76, -v131
	s_add_u32 s4, s4, s1
	v_readlane_b32 s1, v255, 44
	v_add_u32_e32 v34, s0, v166
	v_add_u32_e32 v38, s0, v167
	v_cvt_pk_bf16_f32 v77, v39, v40
	v_exp_f32_e32 v49, v0
	s_addc_u32 s5, s1, 0
	v_and_b32_e32 v0, 0x70, v183
	v_ashrrev_i32_e32 v35, 31, v34
	v_ashrrev_i32_e32 v39, 31, v38
	v_lshl_add_u64 v[140:141], s[4:5], 0, v[0:1]
	v_lshlrev_b64 v[34:35], 11, v[34:35]
	v_lshlrev_b64 v[38:39], 11, v[38:39]
	v_lshl_add_u64 v[138:139], v[140:141], 0, v[34:35]
	v_lshl_add_u64 v[142:143], v[140:141], 0, v[38:39]
	s_barrier
	global_load_dwordx4 v[34:37], v[138:139], off
	global_load_dwordx4 v[38:41], v[142:143], off
	v_add_u32_e32 v0, 0, v0
	v_mad_u64_u32 v[132:133], s[4:5], v166, s86, v[0:1]
	v_mad_u64_u32 v[134:135], s[4:5], v167, s86, v[0:1]
	v_cvt_pk_bf16_f32 v78, v17, v42
	v_fma_f32 v17, v18, s76, -v131
	v_exp_f32_e32 v17, v17
	v_fma_f32 v18, v19, s76, -v131
	v_add_f32_e32 v46, v47, v46
	v_exp_f32_e32 v18, v18
	v_fma_f32 v19, v20, s76, -v131
	v_add_f32_e32 v46, v48, v46
	v_exp_f32_e32 v19, v19
	v_fma_f32 v20, v21, s76, -v131
	v_add_f32_e32 v46, v49, v46
	v_exp_f32_e32 v20, v20
	v_fma_f32 v22, v22, s76, -v131
	v_add_f32_e32 v21, v17, v46
	v_exp_f32_e32 v22, v22
	v_fma_f32 v23, v23, s76, -v131
	v_add_f32_e32 v21, v18, v21
	v_exp_f32_e32 v23, v23
	v_fma_f32 v24, v24, s76, -v131
	v_add_f32_e32 v21, v19, v21
	v_exp_f32_e32 v24, v24
	v_fma_f32 v25, v25, s76, -v131
	v_add_f32_e32 v21, v20, v21
	v_exp_f32_e32 v25, v25
	v_cvt_pk_bf16_f32 v106, v17, v18
	v_fma_f32 v17, v26, s76, -v131
	v_add_f32_e32 v21, v22, v21
	v_exp_f32_e32 v17, v17
	v_fma_f32 v18, v27, s76, -v131
	v_add_f32_e32 v21, v23, v21
	v_cvt_pk_bf16_f32 v107, v19, v20
	v_exp_f32_e32 v18, v18
	v_fma_f32 v19, v28, s76, -v131
	v_add_f32_e32 v21, v24, v21
	v_exp_f32_e32 v19, v19
	v_fma_f32 v20, v29, s76, -v131
	v_add_f32_e32 v21, v25, v21
	v_cvt_pk_bf16_f32 v108, v22, v23
	v_exp_f32_e32 v20, v20
	v_fma_f32 v22, v30, s76, -v131
	v_add_f32_e32 v21, v17, v21
	v_exp_f32_e32 v22, v22
	v_fma_f32 v23, v31, s76, -v131
	v_cvt_pk_bf16_f32 v109, v24, v25
	v_add_f32_e32 v21, v18, v21
	v_exp_f32_e32 v23, v23
	v_fma_f32 v24, v32, s76, -v131
	v_add_f32_e32 v21, v19, v21
	v_exp_f32_e32 v24, v24
	v_fma_f32 v25, v33, s76, -v131
	v_add_f32_e32 v21, v20, v21
	v_exp_f32_e32 v25, v25
	v_fma_f32 v2, v2, s76, -v131
	v_add_f32_e32 v21, v22, v21
	v_exp_f32_e32 v2, v2
	v_fma_f32 v3, v3, s76, -v131
	v_add_f32_e32 v21, v23, v21
	v_exp_f32_e32 v3, v3
	v_fma_f32 v4, v4, s76, -v131
	v_add_f32_e32 v21, v24, v21
	v_exp_f32_e32 v4, v4
	v_fma_f32 v5, v5, s76, -v131
	v_add_f32_e32 v21, v25, v21
	v_exp_f32_e32 v5, v5
	v_fma_f32 v6, v6, s76, -v131
	v_cvt_pk_bf16_f32 v110, v17, v18
	v_add_f32_e32 v17, v2, v21
	v_exp_f32_e32 v6, v6
	v_fma_f32 v7, v7, s76, -v131
	v_add_f32_e32 v17, v3, v17
	v_exp_f32_e32 v7, v7
	v_fma_f32 v8, v8, s76, -v131
	v_add_f32_e32 v0, v4, v17
	s_waitcnt vmcnt(1)
	ds_write_b128 v132, v[34:37]
	s_waitcnt vmcnt(0)
	ds_write_b128 v134, v[38:41]
	s_waitcnt lgkmcnt(0)
	s_barrier
	global_load_dwordx4 v[146:149], v[138:139], off offset:128
	global_load_dwordx4 v[150:153], v[142:143], off offset:128
	v_exp_f32_e32 v8, v8
	v_fma_f32 v9, v9, s76, -v131
	v_cvt_pk_bf16_f32 v119, v119, v120
	v_cvt_pk_bf16_f32 v120, v121, v122
	v_add_f32_e32 v0, v5, v0
	v_exp_f32_e32 v9, v9
	v_cvt_pk_bf16_f32 v122, v2, v3
	v_fma_f32 v2, v10, s76, -v131
	v_add_f32_e32 v0, v6, v0
	v_exp_f32_e32 v2, v2
	v_fma_f32 v3, v11, s76, -v131
	v_cvt_pk_bf16_f32 v121, v123, v124
	v_add_f32_e32 v0, v7, v0
	v_cvt_pk_bf16_f32 v123, v4, v5
	v_exp_f32_e32 v3, v3
	v_fma_f32 v4, v12, s76, -v131
	v_add_f32_e32 v0, v8, v0
	v_exp_f32_e32 v4, v4
	v_fma_f32 v5, v13, s76, -v131
	v_add_f32_e32 v0, v9, v0
	v_cvt_pk_bf16_f32 v124, v6, v7
	v_exp_f32_e32 v5, v5
	v_fma_f32 v6, v14, s76, -v131
	v_add_f32_e32 v0, v2, v0
	v_exp_f32_e32 v6, v6
	v_fma_f32 v7, v15, s76, -v131
	v_cvt_pk_bf16_f32 v125, v8, v9
	v_add_f32_e32 v0, v3, v0
	v_exp_f32_e32 v7, v7
	v_fma_f32 v8, v16, s76, -v131
	v_add_f32_e32 v0, v4, v0
	v_exp_f32_e32 v8, v8
	v_sub_f32_e32 v9, v130, v131
	v_add_f32_e32 v0, v5, v0
	v_exp_f32_e32 v9, v9
	v_add_f32_e32 v0, v6, v0
	v_add_f32_e32 v0, v7, v0
	v_add_f32_e32 v0, v8, v0
	v_add_f32_e32 v0, v9, v0
	v_cvt_pk_bf16_f32 v126, v2, v3
	v_mov_b32_e32 v2, v0
	v_mov_b32_e32 v3, v0
	s_nop 1
	v_permlane32_swap_b32_e32 v2, v3
	v_cmp_eq_u32_e32 vcc, v2, v0
	v_cvt_pk_bf16_f32 v127, v4, v5
	v_cvt_pk_bf16_f32 v128, v6, v7
	v_cndmask_b32_e32 v2, v2, v3, vcc
	v_add_f32_e32 v0, v0, v2
	v_div_scale_f32 v2, s[4:5], v0, v0, 1.0
	v_rcp_f32_e32 v3, v2
	v_mad_u32_u24 v133, v180, s86, v163
	v_cvt_pk_bf16_f32 v129, v8, v9
	v_lshlrev_b32_e32 v18, 2, v181
	v_fma_f32 v4, -v2, v3, 1.0
	v_fmac_f32_e32 v3, v4, v3
	v_div_scale_f32 v4, vcc, 1.0, v0, 1.0
	v_mul_f32_e32 v5, v4, v3
	v_fma_f32 v6, -v2, v5, v4
	v_fmac_f32_e32 v5, v6, v3
	v_fma_f32 v2, -v2, v5, v4
	v_div_fmas_f32 v2, v2, v3, v5
	v_div_fixup_f32 v0, v2, v0, 1.0
	ds_read_b128 v[2:5], v133
	ds_read_b128 v[6:9], v133 offset:4608
	ds_read_b128 v[10:13], v133 offset:9216
	ds_read_b128 v[14:17], v133 offset:13824
	v_cvt_pk_bf16_f32 v111, v19, v20
	v_ashrrev_i32_e32 v19, 31, v18
	v_lshl_add_u64 v[144:145], v[18:19], 1, v[160:161]
	s_mov_b64 s[4:5], 0x4800
	v_lshl_add_u64 v[136:137], v[144:145], 0, s[4:5]
	v_readlane_b32 s4, v255, 45
	v_add_u32_e32 v130, s0, v18
	v_lshlrev_b64 v[18:19], 11, v[158:159]
	v_readlane_b32 s5, v255, 46
	v_cvt_pk_bf16_f32 v71, v50, v51
	v_cvt_pk_bf16_f32 v72, v53, v54
	v_cvt_pk_bf16_f32 v73, v55, v56
	v_cvt_pk_bf16_f32 v79, v43, v44
	v_cvt_pk_bf16_f32 v80, v45, v47
	v_cvt_pk_bf16_f32 v81, v48, v49
	v_cvt_pk_bf16_f32 v112, v22, v23
	v_cvt_pk_bf16_f32 v113, v24, v25
	v_lshl_add_u64 v[168:169], s[4:5], 0, v[18:19]
	ds_read_b128 v[154:157], v133 offset:32
	ds_read_b128 v[158:161], v133 offset:4640
	ds_read_b128 v[162:165], v133 offset:9248
	ds_read_b128 v[170:173], v133 offset:13856
	s_waitcnt lgkmcnt(7)
	v_mfma_f32_32x32x16_bf16 v[50:65], v[2:5], v[114:117], 0
	s_waitcnt lgkmcnt(6)
	v_mfma_f32_32x32x16_bf16 v[34:49], v[6:9], v[114:117], 0
	s_waitcnt lgkmcnt(5)
	v_mfma_f32_32x32x16_bf16 v[18:33], v[10:13], v[114:117], 0
	s_waitcnt lgkmcnt(4)
	v_mfma_f32_32x32x16_bf16 v[2:17], v[14:17], v[114:117], 0
	s_waitcnt lgkmcnt(3)
	v_mfma_f32_32x32x16_bf16 v[50:65], v[154:157], v[118:121], v[50:65]
	s_waitcnt lgkmcnt(2)
	v_mfma_f32_32x32x16_bf16 v[34:49], v[158:161], v[118:121], v[34:49]
	s_waitcnt lgkmcnt(1)
	v_mfma_f32_32x32x16_bf16 v[18:33], v[162:165], v[118:121], v[18:33]
	ds_read_b128 v[154:157], v133 offset:64
	ds_read_b128 v[158:161], v133 offset:4672
	ds_read_b128 v[162:165], v133 offset:9280
	ds_read_b128 v[174:177], v133 offset:13888
	s_waitcnt lgkmcnt(4)
	v_mfma_f32_32x32x16_bf16 v[2:17], v[170:173], v[118:121], v[2:17]
	s_waitcnt lgkmcnt(3)
	v_mfma_f32_32x32x16_bf16 v[50:65], v[154:157], v[82:85], v[50:65]
	s_waitcnt lgkmcnt(2)
	v_mfma_f32_32x32x16_bf16 v[34:49], v[158:161], v[82:85], v[34:49]
	s_waitcnt lgkmcnt(1)
	v_mfma_f32_32x32x16_bf16 v[18:33], v[162:165], v[82:85], v[18:33]
	ds_read_b128 v[154:157], v133 offset:96
	ds_read_b128 v[158:161], v133 offset:4704
	ds_read_b128 v[162:165], v133 offset:9312
	ds_read_b128 v[170:173], v133 offset:13920
	s_waitcnt lgkmcnt(4)
	v_mfma_f32_32x32x16_bf16 v[2:17], v[174:177], v[82:85], v[2:17]
	s_waitcnt lgkmcnt(3)
	v_mfma_f32_32x32x16_bf16 v[50:65], v[154:157], v[86:89], v[50:65]
	s_waitcnt lgkmcnt(2)
	v_mfma_f32_32x32x16_bf16 v[34:49], v[158:161], v[86:89], v[34:49]
	s_waitcnt lgkmcnt(1)
	v_mfma_f32_32x32x16_bf16 v[18:33], v[162:165], v[86:89], v[18:33]
	s_waitcnt lgkmcnt(0)
	v_mfma_f32_32x32x16_bf16 v[2:17], v[170:173], v[86:89], v[2:17]
	s_waitcnt vmcnt(1)
	ds_write_b128 v132, v[146:149] offset:18432
	s_waitcnt vmcnt(0)
	ds_write_b128 v134, v[150:153] offset:18432
	s_waitcnt lgkmcnt(0)
	s_barrier
	global_load_dwordx4 v[146:149], v[138:139], off offset:256
	global_load_dwordx4 v[150:153], v[142:143], off offset:256
	ds_read_b128 v[154:157], v133 offset:18432
	ds_read_b128 v[158:161], v133 offset:23040
	ds_read_b128 v[162:165], v133 offset:27648
	ds_read_b128 v[170:173], v133 offset:32256
	s_waitcnt lgkmcnt(3)
	v_mfma_f32_32x32x16_bf16 v[50:65], v[154:157], v[90:93], v[50:65]
	s_waitcnt lgkmcnt(2)
	v_mfma_f32_32x32x16_bf16 v[34:49], v[158:161], v[90:93], v[34:49]
	s_waitcnt lgkmcnt(1)
	v_mfma_f32_32x32x16_bf16 v[18:33], v[162:165], v[90:93], v[18:33]
	ds_read_b128 v[154:157], v133 offset:18464
	ds_read_b128 v[158:161], v133 offset:23072
	ds_read_b128 v[162:165], v133 offset:27680
	ds_read_b128 v[174:177], v133 offset:32288
	s_waitcnt lgkmcnt(4)
	v_mfma_f32_32x32x16_bf16 v[2:17], v[170:173], v[90:93], v[2:17]
	s_waitcnt lgkmcnt(3)
	v_mfma_f32_32x32x16_bf16 v[50:65], v[154:157], v[94:97], v[50:65]
	s_waitcnt lgkmcnt(2)
	v_mfma_f32_32x32x16_bf16 v[34:49], v[158:161], v[94:97], v[34:49]
	s_waitcnt lgkmcnt(1)
	v_mfma_f32_32x32x16_bf16 v[18:33], v[162:165], v[94:97], v[18:33]
	ds_read_b128 v[154:157], v133 offset:18496
	ds_read_b128 v[158:161], v133 offset:23104
	ds_read_b128 v[162:165], v133 offset:27712
	ds_read_b128 v[170:173], v133 offset:32320
	s_waitcnt lgkmcnt(4)
	v_mfma_f32_32x32x16_bf16 v[2:17], v[174:177], v[94:97], v[2:17]
	s_waitcnt lgkmcnt(3)
	v_mfma_f32_32x32x16_bf16 v[50:65], v[154:157], v[98:101], v[50:65]
	s_waitcnt lgkmcnt(2)
	v_mfma_f32_32x32x16_bf16 v[34:49], v[158:161], v[98:101], v[34:49]
	s_waitcnt lgkmcnt(1)
	v_mfma_f32_32x32x16_bf16 v[18:33], v[162:165], v[98:101], v[18:33]
	ds_read_b128 v[154:157], v133 offset:18528
	ds_read_b128 v[158:161], v133 offset:23136
	ds_read_b128 v[162:165], v133 offset:27744
	ds_read_b128 v[174:177], v133 offset:32352
	s_waitcnt lgkmcnt(4)
	v_mfma_f32_32x32x16_bf16 v[2:17], v[170:173], v[98:101], v[2:17]
	s_waitcnt lgkmcnt(3)
	v_mfma_f32_32x32x16_bf16 v[50:65], v[154:157], v[102:105], v[50:65]
	s_waitcnt lgkmcnt(2)
	v_mfma_f32_32x32x16_bf16 v[34:49], v[158:161], v[102:105], v[34:49]
	s_waitcnt lgkmcnt(1)
	v_mfma_f32_32x32x16_bf16 v[18:33], v[162:165], v[102:105], v[18:33]
	s_waitcnt lgkmcnt(0)
	v_mfma_f32_32x32x16_bf16 v[2:17], v[174:177], v[102:105], v[2:17]
	s_waitcnt vmcnt(1)
	ds_write_b128 v132, v[146:149]
	s_waitcnt vmcnt(0)
	ds_write_b128 v134, v[150:153]
	s_waitcnt lgkmcnt(0)
	s_barrier
	global_load_dwordx4 v[146:149], v[138:139], off offset:384
	global_load_dwordx4 v[150:153], v[142:143], off offset:384
	ds_read_b128 v[154:157], v133
	ds_read_b128 v[158:161], v133 offset:4608
	ds_read_b128 v[162:165], v133 offset:9216
	ds_read_b128 v[170:173], v133 offset:13824
	s_waitcnt lgkmcnt(3)
	v_mfma_f32_32x32x16_bf16 v[50:65], v[154:157], v[66:69], v[50:65]
	s_waitcnt lgkmcnt(2)
	v_mfma_f32_32x32x16_bf16 v[34:49], v[158:161], v[66:69], v[34:49]
	s_waitcnt lgkmcnt(1)
	v_mfma_f32_32x32x16_bf16 v[18:33], v[162:165], v[66:69], v[18:33]
	ds_read_b128 v[154:157], v133 offset:32
	ds_read_b128 v[158:161], v133 offset:4640
	ds_read_b128 v[162:165], v133 offset:9248
	ds_read_b128 v[174:177], v133 offset:13856
	s_waitcnt lgkmcnt(4)
	v_mfma_f32_32x32x16_bf16 v[2:17], v[170:173], v[66:69], v[2:17]
	s_waitcnt lgkmcnt(3)
	v_mfma_f32_32x32x16_bf16 v[50:65], v[154:157], v[70:73], v[50:65]
	s_waitcnt lgkmcnt(2)
	v_mfma_f32_32x32x16_bf16 v[34:49], v[158:161], v[70:73], v[34:49]
	s_waitcnt lgkmcnt(1)
	v_mfma_f32_32x32x16_bf16 v[18:33], v[162:165], v[70:73], v[18:33]
	ds_read_b128 v[154:157], v133 offset:64
	ds_read_b128 v[158:161], v133 offset:4672
	ds_read_b128 v[162:165], v133 offset:9280
	ds_read_b128 v[170:173], v133 offset:13888
	s_waitcnt lgkmcnt(4)
	v_mfma_f32_32x32x16_bf16 v[2:17], v[174:177], v[70:73], v[2:17]
	s_waitcnt lgkmcnt(3)
	v_mfma_f32_32x32x16_bf16 v[50:65], v[154:157], v[74:77], v[50:65]
	s_waitcnt lgkmcnt(2)
	v_mfma_f32_32x32x16_bf16 v[34:49], v[158:161], v[74:77], v[34:49]
	s_waitcnt lgkmcnt(1)
	v_mfma_f32_32x32x16_bf16 v[18:33], v[162:165], v[74:77], v[18:33]
	ds_read_b128 v[154:157], v133 offset:96
	ds_read_b128 v[158:161], v133 offset:4704
	ds_read_b128 v[162:165], v133 offset:9312
	ds_read_b128 v[174:177], v133 offset:13920
	s_waitcnt lgkmcnt(4)
	v_mfma_f32_32x32x16_bf16 v[2:17], v[170:173], v[74:77], v[2:17]
	s_waitcnt lgkmcnt(3)
	v_mfma_f32_32x32x16_bf16 v[50:65], v[154:157], v[78:81], v[50:65]
	s_waitcnt lgkmcnt(2)
	v_mfma_f32_32x32x16_bf16 v[34:49], v[158:161], v[78:81], v[34:49]
	s_waitcnt lgkmcnt(1)
	v_mfma_f32_32x32x16_bf16 v[18:33], v[162:165], v[78:81], v[18:33]
	s_waitcnt lgkmcnt(0)
	v_mfma_f32_32x32x16_bf16 v[2:17], v[174:177], v[78:81], v[2:17]
	s_bitset1_b32 s0, 7
	v_add_u32_e32 v138, s0, v166
	v_ashrrev_i32_e32 v139, 31, v138
	v_add_u32_e32 v142, s0, v167
	v_lshlrev_b64 v[138:139], 11, v[138:139]
	v_ashrrev_i32_e32 v143, 31, v142
	v_lshl_add_u64 v[138:139], v[140:141], 0, v[138:139]
	v_lshlrev_b64 v[142:143], 11, v[142:143]
	s_waitcnt vmcnt(1)
	ds_write_b128 v132, v[146:149] offset:18432
	s_waitcnt vmcnt(0)
	ds_write_b128 v134, v[150:153] offset:18432
	s_waitcnt lgkmcnt(0)
	s_barrier
	v_lshl_add_u64 v[140:141], v[140:141], 0, v[142:143]
	global_load_dwordx4 v[146:149], v[138:139], off
	global_load_dwordx4 v[150:153], v[140:141], off
	ds_read_b128 v[154:157], v133 offset:18432
	ds_read_b128 v[158:161], v133 offset:23040
	ds_read_b128 v[162:165], v133 offset:27648
	ds_read_b128 v[170:173], v133 offset:32256
	s_waitcnt lgkmcnt(3)
	v_mfma_f32_32x32x16_bf16 v[50:65], v[154:157], v[106:109], v[50:65]
	s_waitcnt lgkmcnt(2)
	v_mfma_f32_32x32x16_bf16 v[34:49], v[158:161], v[106:109], v[34:49]
	s_waitcnt lgkmcnt(1)
	v_mfma_f32_32x32x16_bf16 v[18:33], v[162:165], v[106:109], v[18:33]
	ds_read_b128 v[154:157], v133 offset:18464
	ds_read_b128 v[158:161], v133 offset:23072
	ds_read_b128 v[162:165], v133 offset:27680
	ds_read_b128 v[174:177], v133 offset:32288
	s_waitcnt lgkmcnt(4)
	v_mfma_f32_32x32x16_bf16 v[2:17], v[170:173], v[106:109], v[2:17]
	s_waitcnt lgkmcnt(3)
	v_mfma_f32_32x32x16_bf16 v[50:65], v[154:157], v[110:113], v[50:65]
	s_waitcnt lgkmcnt(2)
	v_mfma_f32_32x32x16_bf16 v[34:49], v[158:161], v[110:113], v[34:49]
	s_waitcnt lgkmcnt(1)
	v_mfma_f32_32x32x16_bf16 v[18:33], v[162:165], v[110:113], v[18:33]
	ds_read_b128 v[154:157], v133 offset:18496
	ds_read_b128 v[158:161], v133 offset:23104
	ds_read_b128 v[162:165], v133 offset:27712
	ds_read_b128 v[170:173], v133 offset:32320
	s_waitcnt lgkmcnt(4)
	v_mfma_f32_32x32x16_bf16 v[2:17], v[174:177], v[110:113], v[2:17]
	s_waitcnt lgkmcnt(3)
	v_mfma_f32_32x32x16_bf16 v[50:65], v[154:157], v[122:125], v[50:65]
	s_waitcnt lgkmcnt(2)
	v_mfma_f32_32x32x16_bf16 v[34:49], v[158:161], v[122:125], v[34:49]
	s_waitcnt lgkmcnt(1)
	v_mfma_f32_32x32x16_bf16 v[18:33], v[162:165], v[122:125], v[18:33]
	ds_read_b128 v[154:157], v133 offset:18528
	ds_read_b128 v[158:161], v133 offset:23136
	ds_read_b128 v[162:165], v133 offset:27744
	ds_read_b128 v[174:177], v133 offset:32352
	s_waitcnt lgkmcnt(4)
	v_mfma_f32_32x32x16_bf16 v[2:17], v[170:173], v[122:125], v[2:17]
	s_waitcnt lgkmcnt(3)
	v_mfma_f32_32x32x16_bf16 v[50:65], v[154:157], v[126:129], v[50:65]
	s_waitcnt lgkmcnt(2)
	v_mfma_f32_32x32x16_bf16 v[34:49], v[158:161], v[126:129], v[34:49]
	s_waitcnt lgkmcnt(1)
	v_mfma_f32_32x32x16_bf16 v[18:33], v[162:165], v[126:129], v[18:33]
	s_waitcnt lgkmcnt(0)
	v_mfma_f32_32x32x16_bf16 v[2:17], v[174:177], v[126:129], v[2:17]
	v_add_co_u32_e32 v142, vcc, s84, v144
	s_waitcnt vmcnt(1)
	ds_write_b128 v132, v[146:149]
	s_waitcnt vmcnt(0)
	ds_write_b128 v134, v[150:153]
	v_addc_co_u32_e32 v143, vcc, 0, v145, vcc
	global_load_dwordx2 v[172:173], v[142:143], off offset:2048
	global_load_dwordx2 v[174:175], v[136:137], off offset:16
	global_load_dwordx2 v[170:171], v[136:137], off offset:32
	global_load_dwordx2 v[166:167], v[136:137], off offset:48
	global_load_dwordx2 v[164:165], v[136:137], off offset:64
	global_load_dwordx2 v[162:163], v[136:137], off offset:80
	global_load_dwordx2 v[160:161], v[136:137], off offset:96
	global_load_dwordx2 v[158:159], v[136:137], off offset:112
	global_load_dwordx2 v[156:157], v[136:137], off offset:128
	global_load_dwordx2 v[154:155], v[136:137], off offset:144
	global_load_dwordx2 v[152:153], v[136:137], off offset:160
	global_load_dwordx2 v[150:151], v[136:137], off offset:176
	global_load_dwordx2 v[148:149], v[136:137], off offset:192
	global_load_dwordx2 v[146:147], v[136:137], off offset:208
	global_load_dwordx2 v[144:145], v[136:137], off offset:224
	global_load_dwordx2 v[142:143], v[136:137], off offset:240
	v_pk_mul_f32 v[50:51], v[0:1], v[50:51] op_sel_hi:[0,1]
	v_pk_mul_f32 v[52:53], v[0:1], v[52:53] op_sel_hi:[0,1]
	v_pk_mul_f32 v[54:55], v[0:1], v[54:55] op_sel_hi:[0,1]
	v_pk_mul_f32 v[56:57], v[0:1], v[56:57] op_sel_hi:[0,1]
	v_pk_mul_f32 v[34:35], v[0:1], v[34:35] op_sel_hi:[0,1]
	v_pk_mul_f32 v[36:37], v[0:1], v[36:37] op_sel_hi:[0,1]
	v_pk_mul_f32 v[38:39], v[0:1], v[38:39] op_sel_hi:[0,1]
	v_pk_mul_f32 v[40:41], v[0:1], v[40:41] op_sel_hi:[0,1]
	v_pk_mul_f32 v[18:19], v[0:1], v[18:19] op_sel_hi:[0,1]
	v_pk_mul_f32 v[20:21], v[0:1], v[20:21] op_sel_hi:[0,1]
	v_pk_mul_f32 v[22:23], v[0:1], v[22:23] op_sel_hi:[0,1]
	v_pk_mul_f32 v[24:25], v[0:1], v[24:25] op_sel_hi:[0,1]
	v_pk_mul_f32 v[2:3], v[0:1], v[2:3] op_sel_hi:[0,1]
	v_pk_mul_f32 v[4:5], v[0:1], v[4:5] op_sel_hi:[0,1]
	v_pk_mul_f32 v[6:7], v[0:1], v[6:7] op_sel_hi:[0,1]
	v_pk_mul_f32 v[8:9], v[0:1], v[8:9] op_sel_hi:[0,1]
	s_waitcnt vmcnt(15)
	v_lshlrev_b32_e32 v176, 16, v172
	v_mul_f32_e32 v131, 0xbfb8aa3b, v176
	v_exp_f32_e32 v131, v131
	v_and_b32_e32 v177, 0xffff0000, v172
	v_lshlrev_b32_e32 v172, 16, v173
	v_and_b32_e32 v173, 0xffff0000, v173
	v_add_f32_e32 v131, 1.0, v131
	v_rcp_f32_e32 v178, v131
	v_mul_f32_e32 v131, 0xbfb8aa3b, v177
	v_exp_f32_e32 v131, v131
	s_nop 0
	v_add_f32_e32 v131, 1.0, v131
	v_rcp_f32_e32 v179, v131
	v_ashrrev_i32_e32 v131, 31, v130
	v_lshl_add_u64 v[130:131], v[130:131], 1, v[168:169]
	v_pk_mul_f32 v[176:177], v[178:179], v[176:177]
	s_nop 0
	v_pk_mul_f32 v[50:51], v[50:51], v[176:177]
	s_nop 0
	v_cvt_pk_bf16_f32 v50, v50, v51
	v_mul_f32_e32 v51, 0xbfb8aa3b, v172
	v_exp_f32_e32 v51, v51
	s_nop 0
	v_add_f32_e32 v51, 1.0, v51
	v_rcp_f32_e32 v176, v51
	v_mul_f32_e32 v51, 0xbfb8aa3b, v173
	v_exp_f32_e32 v51, v51
	s_nop 0
	v_add_f32_e32 v51, 1.0, v51
	v_rcp_f32_e32 v177, v51
	s_nop 0
	v_pk_mul_f32 v[172:173], v[176:177], v[172:173]
	s_nop 0
	v_pk_mul_f32 v[52:53], v[52:53], v[172:173]
	s_nop 0
	v_cvt_pk_bf16_f32 v51, v52, v53
	global_store_dwordx2 v[130:131], v[50:51], off
	s_waitcnt vmcnt(15)
	v_lshlrev_b32_e32 v50, 16, v174
	v_and_b32_e32 v51, 0xffff0000, v174
	v_mul_f32_e32 v52, 0xbfb8aa3b, v50
	v_mul_f32_e32 v53, 0xbfb8aa3b, v51
	v_exp_f32_e32 v52, v52
	v_exp_f32_e32 v53, v53
	v_add_f32_e32 v52, 1.0, v52
	v_add_f32_e32 v53, 1.0, v53
	v_rcp_f32_e32 v52, v52
	v_rcp_f32_e32 v53, v53
	s_nop 0
	v_pk_mul_f32 v[50:51], v[52:53], v[50:51]
	s_nop 0
	v_pk_mul_f32 v[50:51], v[54:55], v[50:51]
	v_lshlrev_b32_e32 v52, 16, v175
	v_cvt_pk_bf16_f32 v50, v50, v51
	v_mul_f32_e32 v51, 0xbfb8aa3b, v52
	v_exp_f32_e32 v51, v51
	v_and_b32_e32 v53, 0xffff0000, v175
	v_add_f32_e32 v51, 1.0, v51
	v_rcp_f32_e32 v54, v51
	v_mul_f32_e32 v51, 0xbfb8aa3b, v53
	v_exp_f32_e32 v51, v51
	s_nop 0
	v_add_f32_e32 v51, 1.0, v51
	v_rcp_f32_e32 v55, v51
	s_nop 0
	v_pk_mul_f32 v[52:53], v[54:55], v[52:53]
	s_nop 0
	v_pk_mul_f32 v[52:53], v[56:57], v[52:53]
	v_pk_mul_f32 v[54:55], v[0:1], v[58:59] op_sel_hi:[0,1]
	v_cvt_pk_bf16_f32 v51, v52, v53
	global_store_dwordx2 v[130:131], v[50:51], off offset:16
	s_waitcnt vmcnt(15)
	v_lshlrev_b32_e32 v50, 16, v170
	v_and_b32_e32 v51, 0xffff0000, v170
	v_mul_f32_e32 v52, 0xbfb8aa3b, v50
	v_mul_f32_e32 v53, 0xbfb8aa3b, v51
	v_exp_f32_e32 v52, v52
	v_exp_f32_e32 v53, v53
	v_pk_mul_f32 v[56:57], v[0:1], v[60:61] op_sel_hi:[0,1]
	v_add_f32_e32 v52, 1.0, v52
	v_add_f32_e32 v53, 1.0, v53
	v_rcp_f32_e32 v52, v52
	v_rcp_f32_e32 v53, v53
	s_nop 0
	v_pk_mul_f32 v[50:51], v[52:53], v[50:51]
	s_nop 0
	v_pk_mul_f32 v[50:51], v[54:55], v[50:51]
	v_lshlrev_b32_e32 v52, 16, v171
	v_cvt_pk_bf16_f32 v50, v50, v51
	v_mul_f32_e32 v51, 0xbfb8aa3b, v52
	v_exp_f32_e32 v51, v51
	v_and_b32_e32 v53, 0xffff0000, v171
	v_add_f32_e32 v51, 1.0, v51
	v_rcp_f32_e32 v54, v51
	v_mul_f32_e32 v51, 0xbfb8aa3b, v53
	v_exp_f32_e32 v51, v51
	s_nop 0
	v_add_f32_e32 v51, 1.0, v51
	v_rcp_f32_e32 v55, v51
	s_nop 0
	v_pk_mul_f32 v[52:53], v[54:55], v[52:53]
	s_nop 0
	v_pk_mul_f32 v[52:53], v[56:57], v[52:53]
	v_pk_mul_f32 v[54:55], v[0:1], v[62:63] op_sel_hi:[0,1]
	v_cvt_pk_bf16_f32 v51, v52, v53
	global_store_dwordx2 v[130:131], v[50:51], off offset:32
	s_waitcnt vmcnt(15)
	v_lshlrev_b32_e32 v50, 16, v166
	v_and_b32_e32 v51, 0xffff0000, v166
	v_mul_f32_e32 v52, 0xbfb8aa3b, v50
	v_mul_f32_e32 v53, 0xbfb8aa3b, v51
	v_exp_f32_e32 v52, v52
	v_exp_f32_e32 v53, v53
	v_pk_mul_f32 v[56:57], v[0:1], v[64:65] op_sel_hi:[0,1]
	v_add_f32_e32 v52, 1.0, v52
	v_add_f32_e32 v53, 1.0, v53
	v_rcp_f32_e32 v52, v52
	v_rcp_f32_e32 v53, v53
	s_nop 0
	v_pk_mul_f32 v[50:51], v[52:53], v[50:51]
	s_nop 0
	v_pk_mul_f32 v[50:51], v[54:55], v[50:51]
	v_lshlrev_b32_e32 v52, 16, v167
	v_cvt_pk_bf16_f32 v50, v50, v51
	v_mul_f32_e32 v51, 0xbfb8aa3b, v52
	v_exp_f32_e32 v51, v51
	v_and_b32_e32 v53, 0xffff0000, v167
	v_add_f32_e32 v51, 1.0, v51
	v_rcp_f32_e32 v54, v51
	v_mul_f32_e32 v51, 0xbfb8aa3b, v53
	v_exp_f32_e32 v51, v51
	s_nop 0
	v_add_f32_e32 v51, 1.0, v51
	v_rcp_f32_e32 v55, v51
	s_nop 0
	v_pk_mul_f32 v[52:53], v[54:55], v[52:53]
	s_nop 0
	v_pk_mul_f32 v[52:53], v[56:57], v[52:53]
	s_nop 0
	v_cvt_pk_bf16_f32 v51, v52, v53
	global_store_dwordx2 v[130:131], v[50:51], off offset:48
	s_waitcnt vmcnt(15)
	v_lshlrev_b32_e32 v50, 16, v164
	v_and_b32_e32 v51, 0xffff0000, v164
	v_mul_f32_e32 v52, 0xbfb8aa3b, v50
	v_mul_f32_e32 v53, 0xbfb8aa3b, v51
	v_exp_f32_e32 v52, v52
	v_exp_f32_e32 v53, v53
	v_add_f32_e32 v52, 1.0, v52
	v_add_f32_e32 v53, 1.0, v53
	v_rcp_f32_e32 v52, v52
	v_rcp_f32_e32 v53, v53
	s_nop 0
	v_pk_mul_f32 v[50:51], v[52:53], v[50:51]
	s_nop 0
	v_pk_mul_f32 v[34:35], v[34:35], v[50:51]
	v_lshlrev_b32_e32 v50, 16, v165
	v_cvt_pk_bf16_f32 v34, v34, v35
	v_mul_f32_e32 v35, 0xbfb8aa3b, v50
	v_exp_f32_e32 v35, v35
	v_and_b32_e32 v51, 0xffff0000, v165
	v_add_f32_e32 v35, 1.0, v35
	v_rcp_f32_e32 v52, v35
	v_mul_f32_e32 v35, 0xbfb8aa3b, v51
	v_exp_f32_e32 v35, v35
	s_nop 0
	v_add_f32_e32 v35, 1.0, v35
	v_rcp_f32_e32 v53, v35
	s_nop 0
	v_pk_mul_f32 v[50:51], v[52:53], v[50:51]
	s_nop 0
	v_pk_mul_f32 v[36:37], v[36:37], v[50:51]
	s_nop 0
	v_cvt_pk_bf16_f32 v35, v36, v37
	global_store_dwordx2 v[130:131], v[34:35], off offset:64
	s_waitcnt vmcnt(15)
	v_lshlrev_b32_e32 v34, 16, v162
	v_and_b32_e32 v35, 0xffff0000, v162
	v_mul_f32_e32 v36, 0xbfb8aa3b, v34
	v_mul_f32_e32 v37, 0xbfb8aa3b, v35
	v_exp_f32_e32 v36, v36
	v_exp_f32_e32 v37, v37
	v_add_f32_e32 v36, 1.0, v36
	v_add_f32_e32 v37, 1.0, v37
	v_rcp_f32_e32 v36, v36
	v_rcp_f32_e32 v37, v37
	s_nop 0
	v_pk_mul_f32 v[34:35], v[36:37], v[34:35]
	s_nop 0
	v_pk_mul_f32 v[34:35], v[38:39], v[34:35]
	v_lshlrev_b32_e32 v36, 16, v163
	v_cvt_pk_bf16_f32 v34, v34, v35
	v_mul_f32_e32 v35, 0xbfb8aa3b, v36
	v_exp_f32_e32 v35, v35
	v_and_b32_e32 v37, 0xffff0000, v163
	v_add_f32_e32 v35, 1.0, v35
	v_rcp_f32_e32 v38, v35
	v_mul_f32_e32 v35, 0xbfb8aa3b, v37
	v_exp_f32_e32 v35, v35
	s_nop 0
	v_add_f32_e32 v35, 1.0, v35
	v_rcp_f32_e32 v39, v35
	s_nop 0
	v_pk_mul_f32 v[36:37], v[38:39], v[36:37]
	s_nop 0
	v_pk_mul_f32 v[36:37], v[40:41], v[36:37]
	v_pk_mul_f32 v[38:39], v[0:1], v[42:43] op_sel_hi:[0,1]
	v_cvt_pk_bf16_f32 v35, v36, v37
	global_store_dwordx2 v[130:131], v[34:35], off offset:80
	s_waitcnt vmcnt(15)
	v_lshlrev_b32_e32 v34, 16, v160
	v_and_b32_e32 v35, 0xffff0000, v160
	v_mul_f32_e32 v36, 0xbfb8aa3b, v34
	v_mul_f32_e32 v37, 0xbfb8aa3b, v35
	v_exp_f32_e32 v36, v36
	v_exp_f32_e32 v37, v37
	v_pk_mul_f32 v[40:41], v[0:1], v[44:45] op_sel_hi:[0,1]
	v_add_f32_e32 v36, 1.0, v36
	v_add_f32_e32 v37, 1.0, v37
	v_rcp_f32_e32 v36, v36
	v_rcp_f32_e32 v37, v37
	s_nop 0
	v_pk_mul_f32 v[34:35], v[36:37], v[34:35]
	s_nop 0
	v_pk_mul_f32 v[34:35], v[38:39], v[34:35]
	v_lshlrev_b32_e32 v36, 16, v161
	v_cvt_pk_bf16_f32 v34, v34, v35
	v_mul_f32_e32 v35, 0xbfb8aa3b, v36
	v_exp_f32_e32 v35, v35
	v_and_b32_e32 v37, 0xffff0000, v161
	v_add_f32_e32 v35, 1.0, v35
	v_rcp_f32_e32 v38, v35
	v_mul_f32_e32 v35, 0xbfb8aa3b, v37
	v_exp_f32_e32 v35, v35
	s_nop 0
	v_add_f32_e32 v35, 1.0, v35
	v_rcp_f32_e32 v39, v35
	s_nop 0
	v_pk_mul_f32 v[36:37], v[38:39], v[36:37]
	s_nop 0
	v_pk_mul_f32 v[36:37], v[40:41], v[36:37]
	v_pk_mul_f32 v[38:39], v[0:1], v[46:47] op_sel_hi:[0,1]
	v_cvt_pk_bf16_f32 v35, v36, v37
	global_store_dwordx2 v[130:131], v[34:35], off offset:96
	s_waitcnt vmcnt(15)
	v_lshlrev_b32_e32 v34, 16, v158
	v_and_b32_e32 v35, 0xffff0000, v158
	v_mul_f32_e32 v36, 0xbfb8aa3b, v34
	v_mul_f32_e32 v37, 0xbfb8aa3b, v35
	v_exp_f32_e32 v36, v36
	v_exp_f32_e32 v37, v37
	v_pk_mul_f32 v[40:41], v[0:1], v[48:49] op_sel_hi:[0,1]
	v_add_f32_e32 v36, 1.0, v36
	v_add_f32_e32 v37, 1.0, v37
	v_rcp_f32_e32 v36, v36
	v_rcp_f32_e32 v37, v37
	s_nop 0
	v_pk_mul_f32 v[34:35], v[36:37], v[34:35]
	s_nop 0
	v_pk_mul_f32 v[34:35], v[38:39], v[34:35]
	v_lshlrev_b32_e32 v36, 16, v159
	v_cvt_pk_bf16_f32 v34, v34, v35
	v_mul_f32_e32 v35, 0xbfb8aa3b, v36
	v_exp_f32_e32 v35, v35
	v_and_b32_e32 v37, 0xffff0000, v159
	v_add_f32_e32 v35, 1.0, v35
	v_rcp_f32_e32 v38, v35
	v_mul_f32_e32 v35, 0xbfb8aa3b, v37
	v_exp_f32_e32 v35, v35
	s_nop 0
	v_add_f32_e32 v35, 1.0, v35
	v_rcp_f32_e32 v39, v35
	s_nop 0
	v_pk_mul_f32 v[36:37], v[38:39], v[36:37]
	s_nop 0
	v_pk_mul_f32 v[36:37], v[40:41], v[36:37]
	s_nop 0
	v_cvt_pk_bf16_f32 v35, v36, v37
	global_store_dwordx2 v[130:131], v[34:35], off offset:112
	s_waitcnt vmcnt(15)
	v_lshlrev_b32_e32 v34, 16, v156
	v_and_b32_e32 v35, 0xffff0000, v156
	v_mul_f32_e32 v36, 0xbfb8aa3b, v34
	v_mul_f32_e32 v37, 0xbfb8aa3b, v35
	v_exp_f32_e32 v36, v36
	v_exp_f32_e32 v37, v37
	v_add_f32_e32 v36, 1.0, v36
	v_add_f32_e32 v37, 1.0, v37
	v_rcp_f32_e32 v36, v36
	v_rcp_f32_e32 v37, v37
	s_nop 0
	v_pk_mul_f32 v[34:35], v[36:37], v[34:35]
	s_nop 0
	v_pk_mul_f32 v[18:19], v[18:19], v[34:35]
	v_lshlrev_b32_e32 v34, 16, v157
	v_cvt_pk_bf16_f32 v18, v18, v19
	v_mul_f32_e32 v19, 0xbfb8aa3b, v34
	v_exp_f32_e32 v19, v19
	v_and_b32_e32 v35, 0xffff0000, v157
	v_add_f32_e32 v19, 1.0, v19
	v_rcp_f32_e32 v36, v19
	v_mul_f32_e32 v19, 0xbfb8aa3b, v35
	v_exp_f32_e32 v19, v19
	s_nop 0
	v_add_f32_e32 v19, 1.0, v19
	v_rcp_f32_e32 v37, v19
	s_nop 0
	v_pk_mul_f32 v[34:35], v[36:37], v[34:35]
	s_nop 0
	v_pk_mul_f32 v[20:21], v[20:21], v[34:35]
	s_nop 0
	v_cvt_pk_bf16_f32 v19, v20, v21
	global_store_dwordx2 v[130:131], v[18:19], off offset:128
	s_waitcnt vmcnt(15)
	v_lshlrev_b32_e32 v18, 16, v154
	v_and_b32_e32 v19, 0xffff0000, v154
	v_mul_f32_e32 v20, 0xbfb8aa3b, v18
	v_mul_f32_e32 v21, 0xbfb8aa3b, v19
	v_exp_f32_e32 v20, v20
	v_exp_f32_e32 v21, v21
	v_add_f32_e32 v20, 1.0, v20
	v_add_f32_e32 v21, 1.0, v21
	v_rcp_f32_e32 v20, v20
	v_rcp_f32_e32 v21, v21
	s_nop 0
	v_pk_mul_f32 v[18:19], v[20:21], v[18:19]
	s_nop 0
	v_pk_mul_f32 v[18:19], v[22:23], v[18:19]
	v_lshlrev_b32_e32 v20, 16, v155
	v_cvt_pk_bf16_f32 v18, v18, v19
	v_mul_f32_e32 v19, 0xbfb8aa3b, v20
	v_exp_f32_e32 v19, v19
	v_and_b32_e32 v21, 0xffff0000, v155
	v_add_f32_e32 v19, 1.0, v19
	v_rcp_f32_e32 v22, v19
	v_mul_f32_e32 v19, 0xbfb8aa3b, v21
	v_exp_f32_e32 v19, v19
	s_nop 0
	v_add_f32_e32 v19, 1.0, v19
	v_rcp_f32_e32 v23, v19
	s_nop 0
	v_pk_mul_f32 v[20:21], v[22:23], v[20:21]
	s_nop 0
	v_pk_mul_f32 v[20:21], v[24:25], v[20:21]
	v_pk_mul_f32 v[22:23], v[0:1], v[26:27] op_sel_hi:[0,1]
	v_cvt_pk_bf16_f32 v19, v20, v21
	global_store_dwordx2 v[130:131], v[18:19], off offset:144
	s_waitcnt vmcnt(15)
	v_lshlrev_b32_e32 v18, 16, v152
	v_and_b32_e32 v19, 0xffff0000, v152
	v_mul_f32_e32 v20, 0xbfb8aa3b, v18
	v_mul_f32_e32 v21, 0xbfb8aa3b, v19
	v_exp_f32_e32 v20, v20
	v_exp_f32_e32 v21, v21
	v_pk_mul_f32 v[24:25], v[0:1], v[28:29] op_sel_hi:[0,1]
	v_add_f32_e32 v20, 1.0, v20
	v_add_f32_e32 v21, 1.0, v21
	v_rcp_f32_e32 v20, v20
	v_rcp_f32_e32 v21, v21
	s_nop 0
	v_pk_mul_f32 v[18:19], v[20:21], v[18:19]
	s_nop 0
	v_pk_mul_f32 v[18:19], v[22:23], v[18:19]
	v_lshlrev_b32_e32 v20, 16, v153
	v_cvt_pk_bf16_f32 v18, v18, v19
	v_mul_f32_e32 v19, 0xbfb8aa3b, v20
	v_exp_f32_e32 v19, v19
	v_and_b32_e32 v21, 0xffff0000, v153
	v_add_f32_e32 v19, 1.0, v19
	v_rcp_f32_e32 v22, v19
	v_mul_f32_e32 v19, 0xbfb8aa3b, v21
	v_exp_f32_e32 v19, v19
	s_nop 0
	v_add_f32_e32 v19, 1.0, v19
	v_rcp_f32_e32 v23, v19
	s_nop 0
	v_pk_mul_f32 v[20:21], v[22:23], v[20:21]
	s_nop 0
	v_pk_mul_f32 v[20:21], v[24:25], v[20:21]
	v_pk_mul_f32 v[22:23], v[0:1], v[30:31] op_sel_hi:[0,1]
	v_cvt_pk_bf16_f32 v19, v20, v21
	global_store_dwordx2 v[130:131], v[18:19], off offset:160
	s_waitcnt vmcnt(15)
	v_lshlrev_b32_e32 v18, 16, v150
	v_and_b32_e32 v19, 0xffff0000, v150
	v_mul_f32_e32 v20, 0xbfb8aa3b, v18
	v_mul_f32_e32 v21, 0xbfb8aa3b, v19
	v_exp_f32_e32 v20, v20
	v_exp_f32_e32 v21, v21
	v_pk_mul_f32 v[24:25], v[0:1], v[32:33] op_sel_hi:[0,1]
	v_add_f32_e32 v20, 1.0, v20
	v_add_f32_e32 v21, 1.0, v21
	v_rcp_f32_e32 v20, v20
	v_rcp_f32_e32 v21, v21
	s_nop 0
	v_pk_mul_f32 v[18:19], v[20:21], v[18:19]
	s_nop 0
	v_pk_mul_f32 v[18:19], v[22:23], v[18:19]
	v_lshlrev_b32_e32 v20, 16, v151
	v_cvt_pk_bf16_f32 v18, v18, v19
	v_mul_f32_e32 v19, 0xbfb8aa3b, v20
	v_exp_f32_e32 v19, v19
	v_and_b32_e32 v21, 0xffff0000, v151
	v_add_f32_e32 v19, 1.0, v19
	v_rcp_f32_e32 v22, v19
	v_mul_f32_e32 v19, 0xbfb8aa3b, v21
	v_exp_f32_e32 v19, v19
	s_nop 0
	v_add_f32_e32 v19, 1.0, v19
	v_rcp_f32_e32 v23, v19
	s_nop 0
	v_pk_mul_f32 v[20:21], v[22:23], v[20:21]
	s_nop 0
	v_pk_mul_f32 v[20:21], v[24:25], v[20:21]
	s_nop 0
	v_cvt_pk_bf16_f32 v19, v20, v21
	global_store_dwordx2 v[130:131], v[18:19], off offset:176
	s_waitcnt vmcnt(15)
	v_lshlrev_b32_e32 v18, 16, v148
	v_and_b32_e32 v19, 0xffff0000, v148
	v_mul_f32_e32 v20, 0xbfb8aa3b, v18
	v_mul_f32_e32 v21, 0xbfb8aa3b, v19
	v_exp_f32_e32 v20, v20
	v_exp_f32_e32 v21, v21
	v_add_f32_e32 v20, 1.0, v20
	v_add_f32_e32 v21, 1.0, v21
	v_rcp_f32_e32 v20, v20
	v_rcp_f32_e32 v21, v21
	s_nop 0
	v_pk_mul_f32 v[18:19], v[20:21], v[18:19]
	s_nop 0
	v_pk_mul_f32 v[2:3], v[2:3], v[18:19]
	v_lshlrev_b32_e32 v18, 16, v149
	v_cvt_pk_bf16_f32 v2, v2, v3
	v_mul_f32_e32 v3, 0xbfb8aa3b, v18
	v_exp_f32_e32 v3, v3
	v_and_b32_e32 v19, 0xffff0000, v149
	v_add_f32_e32 v3, 1.0, v3
	v_rcp_f32_e32 v20, v3
	v_mul_f32_e32 v3, 0xbfb8aa3b, v19
	v_exp_f32_e32 v3, v3
	s_nop 0
	v_add_f32_e32 v3, 1.0, v3
	v_rcp_f32_e32 v21, v3
	s_nop 0
	v_pk_mul_f32 v[18:19], v[20:21], v[18:19]
	s_nop 0
	v_pk_mul_f32 v[4:5], v[4:5], v[18:19]
	s_nop 0
	v_cvt_pk_bf16_f32 v3, v4, v5
	global_store_dwordx2 v[130:131], v[2:3], off offset:192
	s_waitcnt vmcnt(15)
	v_lshlrev_b32_e32 v2, 16, v146
	v_and_b32_e32 v3, 0xffff0000, v146
	v_mul_f32_e32 v4, 0xbfb8aa3b, v2
	v_mul_f32_e32 v5, 0xbfb8aa3b, v3
	v_exp_f32_e32 v4, v4
	v_exp_f32_e32 v5, v5
	v_add_f32_e32 v4, 1.0, v4
	v_add_f32_e32 v5, 1.0, v5
	v_rcp_f32_e32 v4, v4
	v_rcp_f32_e32 v5, v5
	s_nop 0
	v_pk_mul_f32 v[2:3], v[4:5], v[2:3]
	s_nop 0
	v_pk_mul_f32 v[2:3], v[6:7], v[2:3]
	v_lshlrev_b32_e32 v4, 16, v147
	v_cvt_pk_bf16_f32 v2, v2, v3
	v_mul_f32_e32 v3, 0xbfb8aa3b, v4
	v_exp_f32_e32 v3, v3
	v_and_b32_e32 v5, 0xffff0000, v147
	v_add_f32_e32 v3, 1.0, v3
	v_rcp_f32_e32 v6, v3
	v_mul_f32_e32 v3, 0xbfb8aa3b, v5
	v_exp_f32_e32 v3, v3
	s_nop 0
	v_add_f32_e32 v3, 1.0, v3
	v_rcp_f32_e32 v7, v3
	s_nop 0
	v_pk_mul_f32 v[4:5], v[6:7], v[4:5]
	s_nop 0
	v_pk_mul_f32 v[4:5], v[8:9], v[4:5]
	v_pk_mul_f32 v[6:7], v[0:1], v[10:11] op_sel_hi:[0,1]
	v_cvt_pk_bf16_f32 v3, v4, v5
	global_store_dwordx2 v[130:131], v[2:3], off offset:208
	s_waitcnt vmcnt(15)
	v_lshlrev_b32_e32 v2, 16, v144
	v_and_b32_e32 v3, 0xffff0000, v144
	v_mul_f32_e32 v4, 0xbfb8aa3b, v2
	v_mul_f32_e32 v5, 0xbfb8aa3b, v3
	v_exp_f32_e32 v4, v4
	v_exp_f32_e32 v5, v5
	v_pk_mul_f32 v[8:9], v[0:1], v[12:13] op_sel_hi:[0,1]
	v_add_f32_e32 v4, 1.0, v4
	v_add_f32_e32 v5, 1.0, v5
	v_rcp_f32_e32 v4, v4
	v_rcp_f32_e32 v5, v5
	s_nop 0
	v_pk_mul_f32 v[2:3], v[4:5], v[2:3]
	s_nop 0
	v_pk_mul_f32 v[2:3], v[6:7], v[2:3]
	v_lshlrev_b32_e32 v4, 16, v145
	v_cvt_pk_bf16_f32 v2, v2, v3
	v_mul_f32_e32 v3, 0xbfb8aa3b, v4
	v_exp_f32_e32 v3, v3
	v_and_b32_e32 v5, 0xffff0000, v145
	v_add_f32_e32 v3, 1.0, v3
	v_rcp_f32_e32 v6, v3
	v_mul_f32_e32 v3, 0xbfb8aa3b, v5
	v_exp_f32_e32 v3, v3
	s_nop 0
	v_add_f32_e32 v3, 1.0, v3
	v_rcp_f32_e32 v7, v3
	s_nop 0
	v_pk_mul_f32 v[4:5], v[6:7], v[4:5]
	s_nop 0
	v_pk_mul_f32 v[4:5], v[8:9], v[4:5]
	v_pk_mul_f32 v[6:7], v[0:1], v[14:15] op_sel_hi:[0,1]
	v_cvt_pk_bf16_f32 v3, v4, v5
	global_store_dwordx2 v[130:131], v[2:3], off offset:224
	s_waitcnt vmcnt(15)
	v_lshlrev_b32_e32 v2, 16, v142
	v_and_b32_e32 v3, 0xffff0000, v142
	v_mul_f32_e32 v4, 0xbfb8aa3b, v2
	v_mul_f32_e32 v5, 0xbfb8aa3b, v3
	v_exp_f32_e32 v4, v4
	v_exp_f32_e32 v5, v5
	v_pk_mul_f32 v[8:9], v[0:1], v[16:17] op_sel_hi:[0,1]
	v_add_f32_e32 v4, 1.0, v4
	v_add_f32_e32 v5, 1.0, v5
	v_rcp_f32_e32 v4, v4
	v_rcp_f32_e32 v5, v5
	s_nop 0
	v_pk_mul_f32 v[2:3], v[4:5], v[2:3]
	s_nop 0
	v_pk_mul_f32 v[2:3], v[6:7], v[2:3]
	v_lshlrev_b32_e32 v4, 16, v143
	v_cvt_pk_bf16_f32 v2, v2, v3
	v_mul_f32_e32 v3, 0xbfb8aa3b, v4
	v_exp_f32_e32 v3, v3
	v_and_b32_e32 v5, 0xffff0000, v143
	v_add_f32_e32 v3, 1.0, v3
	v_rcp_f32_e32 v6, v3
	v_mul_f32_e32 v3, 0xbfb8aa3b, v5
	v_exp_f32_e32 v3, v3
	s_nop 0
	v_add_f32_e32 v3, 1.0, v3
	v_rcp_f32_e32 v7, v3
	s_nop 0
	v_pk_mul_f32 v[4:5], v[6:7], v[4:5]
	s_nop 0
	v_pk_mul_f32 v[4:5], v[8:9], v[4:5]
	s_nop 0
	v_cvt_pk_bf16_f32 v3, v4, v5
	global_store_dwordx2 v[130:131], v[2:3], off offset:240
	s_waitcnt lgkmcnt(0)
	s_barrier
	global_load_dwordx4 v[142:145], v[138:139], off offset:128
	global_load_dwordx4 v[146:149], v[140:141], off offset:128
	ds_read_b128 v[2:5], v133
	ds_read_b128 v[6:9], v133 offset:4608
	ds_read_b128 v[10:13], v133 offset:9216
	ds_read_b128 v[14:17], v133 offset:13824
	ds_read_b128 v[150:153], v133 offset:32
	ds_read_b128 v[154:157], v133 offset:4640
	ds_read_b128 v[158:161], v133 offset:9248
	ds_read_b128 v[162:165], v133 offset:13856
	s_waitcnt lgkmcnt(7)
	v_mfma_f32_32x32x16_bf16 v[50:65], v[2:5], v[114:117], 0
	s_waitcnt lgkmcnt(6)
	v_mfma_f32_32x32x16_bf16 v[34:49], v[6:9], v[114:117], 0
	s_waitcnt lgkmcnt(5)
	v_mfma_f32_32x32x16_bf16 v[18:33], v[10:13], v[114:117], 0
	s_waitcnt lgkmcnt(4)
	v_mfma_f32_32x32x16_bf16 v[2:17], v[14:17], v[114:117], 0
	s_waitcnt lgkmcnt(3)
	v_mfma_f32_32x32x16_bf16 v[50:65], v[150:153], v[118:121], v[50:65]
	s_waitcnt lgkmcnt(2)
	v_mfma_f32_32x32x16_bf16 v[34:49], v[154:157], v[118:121], v[34:49]
	s_waitcnt lgkmcnt(1)
	v_mfma_f32_32x32x16_bf16 v[18:33], v[158:161], v[118:121], v[18:33]
	ds_read_b128 v[114:117], v133 offset:64
	ds_read_b128 v[150:153], v133 offset:4672
	ds_read_b128 v[154:157], v133 offset:9280
	ds_read_b128 v[158:161], v133 offset:13888
	s_waitcnt lgkmcnt(4)
	v_mfma_f32_32x32x16_bf16 v[2:17], v[162:165], v[118:121], v[2:17]
	s_waitcnt lgkmcnt(3)
	v_mfma_f32_32x32x16_bf16 v[50:65], v[114:117], v[82:85], v[50:65]
	s_waitcnt lgkmcnt(2)
	v_mfma_f32_32x32x16_bf16 v[34:49], v[150:153], v[82:85], v[34:49]
	s_waitcnt lgkmcnt(1)
	v_mfma_f32_32x32x16_bf16 v[18:33], v[154:157], v[82:85], v[18:33]
	ds_read_b128 v[114:117], v133 offset:96
	ds_read_b128 v[118:121], v133 offset:4704
	ds_read_b128 v[150:153], v133 offset:9312
	ds_read_b128 v[154:157], v133 offset:13920
	s_waitcnt lgkmcnt(4)
	v_mfma_f32_32x32x16_bf16 v[2:17], v[158:161], v[82:85], v[2:17]
	s_waitcnt lgkmcnt(3)
	v_mfma_f32_32x32x16_bf16 v[50:65], v[114:117], v[86:89], v[50:65]
	s_waitcnt lgkmcnt(2)
	v_mfma_f32_32x32x16_bf16 v[34:49], v[118:121], v[86:89], v[34:49]
	s_waitcnt lgkmcnt(1)
	v_mfma_f32_32x32x16_bf16 v[18:33], v[150:153], v[86:89], v[18:33]
	s_waitcnt lgkmcnt(0)
	v_mfma_f32_32x32x16_bf16 v[2:17], v[154:157], v[86:89], v[2:17]
	s_waitcnt vmcnt(1)
	ds_write_b128 v132, v[142:145] offset:18432
	s_waitcnt vmcnt(0)
	ds_write_b128 v134, v[146:149] offset:18432
	s_waitcnt lgkmcnt(0)
	s_barrier
	global_load_dwordx4 v[82:85], v[138:139], off offset:256
	global_load_dwordx4 v[86:89], v[140:141], off offset:256
	ds_read_b128 v[114:117], v133 offset:18432
	ds_read_b128 v[118:121], v133 offset:23040
	ds_read_b128 v[142:145], v133 offset:27648
	ds_read_b128 v[146:149], v133 offset:32256
	s_waitcnt lgkmcnt(3)
	v_mfma_f32_32x32x16_bf16 v[50:65], v[114:117], v[90:93], v[50:65]
	s_waitcnt lgkmcnt(2)
	v_mfma_f32_32x32x16_bf16 v[34:49], v[118:121], v[90:93], v[34:49]
	s_waitcnt lgkmcnt(1)
	v_mfma_f32_32x32x16_bf16 v[18:33], v[142:145], v[90:93], v[18:33]
	ds_read_b128 v[114:117], v133 offset:18464
	ds_read_b128 v[118:121], v133 offset:23072
	ds_read_b128 v[142:145], v133 offset:27680
	ds_read_b128 v[150:153], v133 offset:32288
	s_waitcnt lgkmcnt(4)
	v_mfma_f32_32x32x16_bf16 v[2:17], v[146:149], v[90:93], v[2:17]
	s_waitcnt lgkmcnt(3)
	v_mfma_f32_32x32x16_bf16 v[50:65], v[114:117], v[94:97], v[50:65]
	s_waitcnt lgkmcnt(2)
	v_mfma_f32_32x32x16_bf16 v[34:49], v[118:121], v[94:97], v[34:49]
	s_waitcnt lgkmcnt(1)
	v_mfma_f32_32x32x16_bf16 v[18:33], v[142:145], v[94:97], v[18:33]
	ds_read_b128 v[90:93], v133 offset:18496
	ds_read_b128 v[114:117], v133 offset:23104
	ds_read_b128 v[118:121], v133 offset:27712
	ds_read_b128 v[142:145], v133 offset:32320
	s_waitcnt lgkmcnt(4)
	v_mfma_f32_32x32x16_bf16 v[2:17], v[150:153], v[94:97], v[2:17]
	s_waitcnt lgkmcnt(3)
	v_mfma_f32_32x32x16_bf16 v[50:65], v[90:93], v[98:101], v[50:65]
	s_waitcnt lgkmcnt(2)
	v_mfma_f32_32x32x16_bf16 v[34:49], v[114:117], v[98:101], v[34:49]
	s_waitcnt lgkmcnt(1)
	v_mfma_f32_32x32x16_bf16 v[18:33], v[118:121], v[98:101], v[18:33]
	ds_read_b128 v[90:93], v133 offset:18528
	ds_read_b128 v[94:97], v133 offset:23136
	ds_read_b128 v[114:117], v133 offset:27744
	ds_read_b128 v[118:121], v133 offset:32352
	s_waitcnt lgkmcnt(4)
	v_mfma_f32_32x32x16_bf16 v[2:17], v[142:145], v[98:101], v[2:17]
	s_waitcnt lgkmcnt(3)
	v_mfma_f32_32x32x16_bf16 v[50:65], v[90:93], v[102:105], v[50:65]
	s_waitcnt lgkmcnt(2)
	v_mfma_f32_32x32x16_bf16 v[34:49], v[94:97], v[102:105], v[34:49]
	s_waitcnt lgkmcnt(1)
	v_mfma_f32_32x32x16_bf16 v[18:33], v[114:117], v[102:105], v[18:33]
	s_waitcnt lgkmcnt(0)
	v_mfma_f32_32x32x16_bf16 v[2:17], v[118:121], v[102:105], v[2:17]
	s_waitcnt vmcnt(1)
	ds_write_b128 v132, v[82:85]
	s_waitcnt vmcnt(0)
	ds_write_b128 v134, v[86:89]
	s_waitcnt lgkmcnt(0)
	s_barrier
	global_load_dwordx4 v[82:85], v[138:139], off offset:384
	global_load_dwordx4 v[86:89], v[140:141], off offset:384
	ds_read_b128 v[90:93], v133
	ds_read_b128 v[94:97], v133 offset:4608
	ds_read_b128 v[98:101], v133 offset:9216
	ds_read_b128 v[102:105], v133 offset:13824
	s_waitcnt lgkmcnt(3)
	v_mfma_f32_32x32x16_bf16 v[50:65], v[90:93], v[66:69], v[50:65]
	s_waitcnt lgkmcnt(2)
	v_mfma_f32_32x32x16_bf16 v[34:49], v[94:97], v[66:69], v[34:49]
	s_waitcnt lgkmcnt(1)
	v_mfma_f32_32x32x16_bf16 v[18:33], v[98:101], v[66:69], v[18:33]
	ds_read_b128 v[90:93], v133 offset:32
	ds_read_b128 v[94:97], v133 offset:4640
	ds_read_b128 v[98:101], v133 offset:9248
	ds_read_b128 v[114:117], v133 offset:13856
	s_waitcnt lgkmcnt(4)
	v_mfma_f32_32x32x16_bf16 v[2:17], v[102:105], v[66:69], v[2:17]
	s_waitcnt lgkmcnt(3)
	v_mfma_f32_32x32x16_bf16 v[50:65], v[90:93], v[70:73], v[50:65]
	s_waitcnt lgkmcnt(2)
	v_mfma_f32_32x32x16_bf16 v[34:49], v[94:97], v[70:73], v[34:49]
	s_waitcnt lgkmcnt(1)
	v_mfma_f32_32x32x16_bf16 v[18:33], v[98:101], v[70:73], v[18:33]
	ds_read_b128 v[66:69], v133 offset:64
	ds_read_b128 v[90:93], v133 offset:4672
	ds_read_b128 v[94:97], v133 offset:9280
	ds_read_b128 v[98:101], v133 offset:13888
	s_waitcnt lgkmcnt(4)
	v_mfma_f32_32x32x16_bf16 v[2:17], v[114:117], v[70:73], v[2:17]
	s_waitcnt lgkmcnt(3)
	v_mfma_f32_32x32x16_bf16 v[50:65], v[66:69], v[74:77], v[50:65]
	s_waitcnt lgkmcnt(2)
	v_mfma_f32_32x32x16_bf16 v[34:49], v[90:93], v[74:77], v[34:49]
	s_waitcnt lgkmcnt(1)
	v_mfma_f32_32x32x16_bf16 v[18:33], v[94:97], v[74:77], v[18:33]
	ds_read_b128 v[66:69], v133 offset:96
	ds_read_b128 v[70:73], v133 offset:4704
	ds_read_b128 v[90:93], v133 offset:9312
	ds_read_b128 v[94:97], v133 offset:13920
	s_waitcnt lgkmcnt(4)
	v_mfma_f32_32x32x16_bf16 v[2:17], v[98:101], v[74:77], v[2:17]
	s_waitcnt lgkmcnt(3)
	v_mfma_f32_32x32x16_bf16 v[50:65], v[66:69], v[78:81], v[50:65]
	s_waitcnt lgkmcnt(2)
	v_mfma_f32_32x32x16_bf16 v[34:49], v[70:73], v[78:81], v[34:49]
	s_waitcnt lgkmcnt(1)
	v_mfma_f32_32x32x16_bf16 v[18:33], v[90:93], v[78:81], v[18:33]
	s_waitcnt lgkmcnt(0)
	v_mfma_f32_32x32x16_bf16 v[2:17], v[94:97], v[78:81], v[2:17]
	s_waitcnt vmcnt(1)
	ds_write_b128 v132, v[82:85] offset:18432
	s_waitcnt vmcnt(0)
	ds_write_b128 v134, v[86:89] offset:18432
	s_waitcnt lgkmcnt(0)
	s_barrier
	ds_read_b128 v[66:69], v133 offset:18432
	ds_read_b128 v[70:73], v133 offset:23040
	ds_read_b128 v[74:77], v133 offset:27648
	ds_read_b128 v[78:81], v133 offset:32256
	s_waitcnt lgkmcnt(3)
	v_mfma_f32_32x32x16_bf16 v[50:65], v[66:69], v[106:109], v[50:65]
	s_waitcnt lgkmcnt(2)
	v_mfma_f32_32x32x16_bf16 v[34:49], v[70:73], v[106:109], v[34:49]
	s_waitcnt lgkmcnt(1)
	v_mfma_f32_32x32x16_bf16 v[18:33], v[74:77], v[106:109], v[18:33]
	ds_read_b128 v[66:69], v133 offset:18464
	ds_read_b128 v[70:73], v133 offset:23072
	ds_read_b128 v[74:77], v133 offset:27680
	ds_read_b128 v[82:85], v133 offset:32288
	s_waitcnt lgkmcnt(4)
	v_mfma_f32_32x32x16_bf16 v[2:17], v[78:81], v[106:109], v[2:17]
	s_waitcnt lgkmcnt(3)
	v_mfma_f32_32x32x16_bf16 v[50:65], v[66:69], v[110:113], v[50:65]
	s_waitcnt lgkmcnt(2)
	v_mfma_f32_32x32x16_bf16 v[34:49], v[70:73], v[110:113], v[34:49]
	s_waitcnt lgkmcnt(1)
	v_mfma_f32_32x32x16_bf16 v[18:33], v[74:77], v[110:113], v[18:33]
	ds_read_b128 v[66:69], v133 offset:18496
	ds_read_b128 v[70:73], v133 offset:23104
	ds_read_b128 v[74:77], v133 offset:27712
	ds_read_b128 v[78:81], v133 offset:32320
	s_waitcnt lgkmcnt(4)
	v_mfma_f32_32x32x16_bf16 v[2:17], v[82:85], v[110:113], v[2:17]
	s_waitcnt lgkmcnt(3)
	v_mfma_f32_32x32x16_bf16 v[50:65], v[66:69], v[122:125], v[50:65]
	s_waitcnt lgkmcnt(2)
	v_mfma_f32_32x32x16_bf16 v[34:49], v[70:73], v[122:125], v[34:49]
	s_waitcnt lgkmcnt(1)
	v_mfma_f32_32x32x16_bf16 v[18:33], v[74:77], v[122:125], v[18:33]
	ds_read_b128 v[66:69], v133 offset:18528
	ds_read_b128 v[70:73], v133 offset:23136
	ds_read_b128 v[74:77], v133 offset:27744
	ds_read_b128 v[82:85], v133 offset:32352
	s_waitcnt lgkmcnt(4)
	v_mfma_f32_32x32x16_bf16 v[2:17], v[78:81], v[122:125], v[2:17]
	s_waitcnt lgkmcnt(3)
	v_mfma_f32_32x32x16_bf16 v[50:65], v[66:69], v[126:129], v[50:65]
	s_waitcnt lgkmcnt(2)
	v_mfma_f32_32x32x16_bf16 v[34:49], v[70:73], v[126:129], v[34:49]
	s_waitcnt lgkmcnt(1)
	v_mfma_f32_32x32x16_bf16 v[18:33], v[74:77], v[126:129], v[18:33]
	s_waitcnt lgkmcnt(0)
	v_mfma_f32_32x32x16_bf16 v[2:17], v[82:85], v[126:129], v[2:17]
	global_load_dwordx2 v[94:95], v[136:137], off offset:256
	global_load_dwordx2 v[96:97], v[136:137], off offset:272
	global_load_dwordx2 v[92:93], v[136:137], off offset:288
	global_load_dwordx2 v[90:91], v[136:137], off offset:304
	global_load_dwordx2 v[88:89], v[136:137], off offset:320
	global_load_dwordx2 v[86:87], v[136:137], off offset:336
	global_load_dwordx2 v[84:85], v[136:137], off offset:352
	global_load_dwordx2 v[82:83], v[136:137], off offset:368
	global_load_dwordx2 v[80:81], v[136:137], off offset:384
	global_load_dwordx2 v[78:79], v[136:137], off offset:400
	global_load_dwordx2 v[76:77], v[136:137], off offset:416
	global_load_dwordx2 v[74:75], v[136:137], off offset:432
	global_load_dwordx2 v[72:73], v[136:137], off offset:448
	global_load_dwordx2 v[70:71], v[136:137], off offset:464
	global_load_dwordx2 v[68:69], v[136:137], off offset:480
	global_load_dwordx2 v[66:67], v[136:137], off offset:496
	v_pk_mul_f32 v[50:51], v[0:1], v[50:51] op_sel_hi:[0,1]
	v_pk_mul_f32 v[52:53], v[0:1], v[52:53] op_sel_hi:[0,1]
	v_pk_mul_f32 v[54:55], v[0:1], v[54:55] op_sel_hi:[0,1]
	v_pk_mul_f32 v[56:57], v[0:1], v[56:57] op_sel_hi:[0,1]
	v_pk_mul_f32 v[34:35], v[0:1], v[34:35] op_sel_hi:[0,1]
	v_pk_mul_f32 v[36:37], v[0:1], v[36:37] op_sel_hi:[0,1]
	v_pk_mul_f32 v[38:39], v[0:1], v[38:39] op_sel_hi:[0,1]
	v_pk_mul_f32 v[40:41], v[0:1], v[40:41] op_sel_hi:[0,1]
	v_pk_mul_f32 v[18:19], v[0:1], v[18:19] op_sel_hi:[0,1]
	v_pk_mul_f32 v[20:21], v[0:1], v[20:21] op_sel_hi:[0,1]
	v_pk_mul_f32 v[22:23], v[0:1], v[22:23] op_sel_hi:[0,1]
	v_pk_mul_f32 v[24:25], v[0:1], v[24:25] op_sel_hi:[0,1]
	v_pk_mul_f32 v[2:3], v[0:1], v[2:3] op_sel_hi:[0,1]
	v_pk_mul_f32 v[4:5], v[0:1], v[4:5] op_sel_hi:[0,1]
	v_pk_mul_f32 v[6:7], v[0:1], v[6:7] op_sel_hi:[0,1]
	v_pk_mul_f32 v[8:9], v[0:1], v[8:9] op_sel_hi:[0,1]
	s_mov_b64 s[0:1], 0
	s_waitcnt vmcnt(15)
	v_lshlrev_b32_e32 v98, 16, v94
	v_and_b32_e32 v99, 0xffff0000, v94
	v_mul_f32_e32 v94, 0xbfb8aa3b, v98
	v_exp_f32_e32 v94, v94
	s_nop 0
	v_add_f32_e32 v94, 1.0, v94
	v_rcp_f32_e32 v100, v94
	v_mul_f32_e32 v94, 0xbfb8aa3b, v99
	v_exp_f32_e32 v94, v94
	s_nop 0
	v_add_f32_e32 v94, 1.0, v94
	v_rcp_f32_e32 v101, v94
	v_lshlrev_b32_e32 v94, 16, v95
	v_and_b32_e32 v95, 0xffff0000, v95
	v_pk_mul_f32 v[98:99], v[100:101], v[98:99]
	s_nop 0
	v_pk_mul_f32 v[50:51], v[50:51], v[98:99]
	s_nop 0
	v_cvt_pk_bf16_f32 v50, v50, v51
	v_mul_f32_e32 v51, 0xbfb8aa3b, v94
	v_exp_f32_e32 v51, v51
	s_nop 0
	v_add_f32_e32 v51, 1.0, v51
	v_rcp_f32_e32 v98, v51
	v_mul_f32_e32 v51, 0xbfb8aa3b, v95
	v_exp_f32_e32 v51, v51
	s_nop 0
	v_add_f32_e32 v51, 1.0, v51
	v_rcp_f32_e32 v99, v51
	s_nop 0
	v_pk_mul_f32 v[94:95], v[98:99], v[94:95]
	s_nop 0
	v_pk_mul_f32 v[52:53], v[52:53], v[94:95]
	s_nop 0
	v_cvt_pk_bf16_f32 v51, v52, v53
	global_store_dwordx2 v[130:131], v[50:51], off offset:256
	s_waitcnt vmcnt(15)
	v_lshlrev_b32_e32 v50, 16, v96
	v_and_b32_e32 v51, 0xffff0000, v96
	v_mul_f32_e32 v52, 0xbfb8aa3b, v50
	v_mul_f32_e32 v53, 0xbfb8aa3b, v51
	v_exp_f32_e32 v52, v52
	v_exp_f32_e32 v53, v53
	v_add_f32_e32 v52, 1.0, v52
	v_add_f32_e32 v53, 1.0, v53
	v_rcp_f32_e32 v52, v52
	v_rcp_f32_e32 v53, v53
	s_nop 0
	v_pk_mul_f32 v[50:51], v[52:53], v[50:51]
	s_nop 0
	v_pk_mul_f32 v[50:51], v[54:55], v[50:51]
	v_lshlrev_b32_e32 v52, 16, v97
	v_cvt_pk_bf16_f32 v50, v50, v51
	v_mul_f32_e32 v51, 0xbfb8aa3b, v52
	v_exp_f32_e32 v51, v51
	v_and_b32_e32 v53, 0xffff0000, v97
	v_add_f32_e32 v51, 1.0, v51
	v_rcp_f32_e32 v54, v51
	v_mul_f32_e32 v51, 0xbfb8aa3b, v53
	v_exp_f32_e32 v51, v51
	s_nop 0
	v_add_f32_e32 v51, 1.0, v51
	v_rcp_f32_e32 v55, v51
	s_nop 0
	v_pk_mul_f32 v[52:53], v[54:55], v[52:53]
	s_nop 0
	v_pk_mul_f32 v[52:53], v[56:57], v[52:53]
	v_pk_mul_f32 v[54:55], v[0:1], v[58:59] op_sel_hi:[0,1]
	v_cvt_pk_bf16_f32 v51, v52, v53
	global_store_dwordx2 v[130:131], v[50:51], off offset:272
	s_waitcnt vmcnt(15)
	v_lshlrev_b32_e32 v50, 16, v92
	v_and_b32_e32 v51, 0xffff0000, v92
	v_mul_f32_e32 v52, 0xbfb8aa3b, v50
	v_mul_f32_e32 v53, 0xbfb8aa3b, v51
	v_exp_f32_e32 v52, v52
	v_exp_f32_e32 v53, v53
	v_pk_mul_f32 v[56:57], v[0:1], v[60:61] op_sel_hi:[0,1]
	v_add_f32_e32 v52, 1.0, v52
	v_add_f32_e32 v53, 1.0, v53
	v_rcp_f32_e32 v52, v52
	v_rcp_f32_e32 v53, v53
	s_nop 0
	v_pk_mul_f32 v[50:51], v[52:53], v[50:51]
	s_nop 0
	v_pk_mul_f32 v[50:51], v[54:55], v[50:51]
	v_lshlrev_b32_e32 v52, 16, v93
	v_cvt_pk_bf16_f32 v50, v50, v51
	v_mul_f32_e32 v51, 0xbfb8aa3b, v52
	v_exp_f32_e32 v51, v51
	v_and_b32_e32 v53, 0xffff0000, v93
	v_add_f32_e32 v51, 1.0, v51
	v_rcp_f32_e32 v54, v51
	v_mul_f32_e32 v51, 0xbfb8aa3b, v53
	v_exp_f32_e32 v51, v51
	s_nop 0
	v_add_f32_e32 v51, 1.0, v51
	v_rcp_f32_e32 v55, v51
	s_nop 0
	v_pk_mul_f32 v[52:53], v[54:55], v[52:53]
	s_nop 0
	v_pk_mul_f32 v[52:53], v[56:57], v[52:53]
	v_pk_mul_f32 v[54:55], v[0:1], v[62:63] op_sel_hi:[0,1]
	v_cvt_pk_bf16_f32 v51, v52, v53
	global_store_dwordx2 v[130:131], v[50:51], off offset:288
	s_waitcnt vmcnt(15)
	v_lshlrev_b32_e32 v50, 16, v90
	v_and_b32_e32 v51, 0xffff0000, v90
	v_mul_f32_e32 v52, 0xbfb8aa3b, v50
	v_mul_f32_e32 v53, 0xbfb8aa3b, v51
	v_exp_f32_e32 v52, v52
	v_exp_f32_e32 v53, v53
	v_pk_mul_f32 v[56:57], v[0:1], v[64:65] op_sel_hi:[0,1]
	v_add_f32_e32 v52, 1.0, v52
	v_add_f32_e32 v53, 1.0, v53
	v_rcp_f32_e32 v52, v52
	v_rcp_f32_e32 v53, v53
	s_nop 0
	v_pk_mul_f32 v[50:51], v[52:53], v[50:51]
	s_nop 0
	v_pk_mul_f32 v[50:51], v[54:55], v[50:51]
	v_lshlrev_b32_e32 v52, 16, v91
	v_cvt_pk_bf16_f32 v50, v50, v51
	v_mul_f32_e32 v51, 0xbfb8aa3b, v52
	v_exp_f32_e32 v51, v51
	v_and_b32_e32 v53, 0xffff0000, v91
	v_add_f32_e32 v51, 1.0, v51
	v_rcp_f32_e32 v54, v51
	v_mul_f32_e32 v51, 0xbfb8aa3b, v53
	v_exp_f32_e32 v51, v51
	s_nop 0
	v_add_f32_e32 v51, 1.0, v51
	v_rcp_f32_e32 v55, v51
	s_nop 0
	v_pk_mul_f32 v[52:53], v[54:55], v[52:53]
	s_nop 0
	v_pk_mul_f32 v[52:53], v[56:57], v[52:53]
	s_nop 0
	v_cvt_pk_bf16_f32 v51, v52, v53
	global_store_dwordx2 v[130:131], v[50:51], off offset:304
	s_waitcnt vmcnt(15)
	v_lshlrev_b32_e32 v50, 16, v88
	v_and_b32_e32 v51, 0xffff0000, v88
	v_mul_f32_e32 v52, 0xbfb8aa3b, v50
	v_mul_f32_e32 v53, 0xbfb8aa3b, v51
	v_exp_f32_e32 v52, v52
	v_exp_f32_e32 v53, v53
	v_add_f32_e32 v52, 1.0, v52
	v_add_f32_e32 v53, 1.0, v53
	v_rcp_f32_e32 v52, v52
	v_rcp_f32_e32 v53, v53
	s_nop 0
	v_pk_mul_f32 v[50:51], v[52:53], v[50:51]
	s_nop 0
	v_pk_mul_f32 v[34:35], v[34:35], v[50:51]
	v_lshlrev_b32_e32 v50, 16, v89
	v_cvt_pk_bf16_f32 v34, v34, v35
	v_mul_f32_e32 v35, 0xbfb8aa3b, v50
	v_exp_f32_e32 v35, v35
	v_and_b32_e32 v51, 0xffff0000, v89
	v_add_f32_e32 v35, 1.0, v35
	v_rcp_f32_e32 v52, v35
	v_mul_f32_e32 v35, 0xbfb8aa3b, v51
	v_exp_f32_e32 v35, v35
	s_nop 0
	v_add_f32_e32 v35, 1.0, v35
	v_rcp_f32_e32 v53, v35
	s_nop 0
	v_pk_mul_f32 v[50:51], v[52:53], v[50:51]
	s_nop 0
	v_pk_mul_f32 v[36:37], v[36:37], v[50:51]
	s_nop 0
	v_cvt_pk_bf16_f32 v35, v36, v37
	global_store_dwordx2 v[130:131], v[34:35], off offset:320
	s_waitcnt vmcnt(15)
	v_lshlrev_b32_e32 v34, 16, v86
	v_and_b32_e32 v35, 0xffff0000, v86
	v_mul_f32_e32 v36, 0xbfb8aa3b, v34
	v_mul_f32_e32 v37, 0xbfb8aa3b, v35
	v_exp_f32_e32 v36, v36
	v_exp_f32_e32 v37, v37
	v_add_f32_e32 v36, 1.0, v36
	v_add_f32_e32 v37, 1.0, v37
	v_rcp_f32_e32 v36, v36
	v_rcp_f32_e32 v37, v37
	s_nop 0
	v_pk_mul_f32 v[34:35], v[36:37], v[34:35]
	s_nop 0
	v_pk_mul_f32 v[34:35], v[38:39], v[34:35]
	v_lshlrev_b32_e32 v36, 16, v87
	v_cvt_pk_bf16_f32 v34, v34, v35
	v_mul_f32_e32 v35, 0xbfb8aa3b, v36
	v_exp_f32_e32 v35, v35
	v_and_b32_e32 v37, 0xffff0000, v87
	v_add_f32_e32 v35, 1.0, v35
	v_rcp_f32_e32 v38, v35
	v_mul_f32_e32 v35, 0xbfb8aa3b, v37
	v_exp_f32_e32 v35, v35
	s_nop 0
	v_add_f32_e32 v35, 1.0, v35
	v_rcp_f32_e32 v39, v35
	s_nop 0
	v_pk_mul_f32 v[36:37], v[38:39], v[36:37]
	s_nop 0
	v_pk_mul_f32 v[36:37], v[40:41], v[36:37]
	v_pk_mul_f32 v[38:39], v[0:1], v[42:43] op_sel_hi:[0,1]
	v_cvt_pk_bf16_f32 v35, v36, v37
	global_store_dwordx2 v[130:131], v[34:35], off offset:336
	s_waitcnt vmcnt(15)
	v_lshlrev_b32_e32 v34, 16, v84
	v_and_b32_e32 v35, 0xffff0000, v84
	v_mul_f32_e32 v36, 0xbfb8aa3b, v34
	v_mul_f32_e32 v37, 0xbfb8aa3b, v35
	v_exp_f32_e32 v36, v36
	v_exp_f32_e32 v37, v37
	v_pk_mul_f32 v[40:41], v[0:1], v[44:45] op_sel_hi:[0,1]
	v_add_f32_e32 v36, 1.0, v36
	v_add_f32_e32 v37, 1.0, v37
	v_rcp_f32_e32 v36, v36
	v_rcp_f32_e32 v37, v37
	s_nop 0
	v_pk_mul_f32 v[34:35], v[36:37], v[34:35]
	s_nop 0
	v_pk_mul_f32 v[34:35], v[38:39], v[34:35]
	v_lshlrev_b32_e32 v36, 16, v85
	v_cvt_pk_bf16_f32 v34, v34, v35
	v_mul_f32_e32 v35, 0xbfb8aa3b, v36
	v_exp_f32_e32 v35, v35
	v_and_b32_e32 v37, 0xffff0000, v85
	v_add_f32_e32 v35, 1.0, v35
	v_rcp_f32_e32 v38, v35
	v_mul_f32_e32 v35, 0xbfb8aa3b, v37
	v_exp_f32_e32 v35, v35
	s_nop 0
	v_add_f32_e32 v35, 1.0, v35
	v_rcp_f32_e32 v39, v35
	s_nop 0
	v_pk_mul_f32 v[36:37], v[38:39], v[36:37]
	s_nop 0
	v_pk_mul_f32 v[36:37], v[40:41], v[36:37]
	v_pk_mul_f32 v[38:39], v[0:1], v[46:47] op_sel_hi:[0,1]
	v_cvt_pk_bf16_f32 v35, v36, v37
	global_store_dwordx2 v[130:131], v[34:35], off offset:352
	s_waitcnt vmcnt(15)
	v_lshlrev_b32_e32 v34, 16, v82
	v_and_b32_e32 v35, 0xffff0000, v82
	v_mul_f32_e32 v36, 0xbfb8aa3b, v34
	v_mul_f32_e32 v37, 0xbfb8aa3b, v35
	v_exp_f32_e32 v36, v36
	v_exp_f32_e32 v37, v37
	v_pk_mul_f32 v[40:41], v[0:1], v[48:49] op_sel_hi:[0,1]
	v_add_f32_e32 v36, 1.0, v36
	v_add_f32_e32 v37, 1.0, v37
	v_rcp_f32_e32 v36, v36
	v_rcp_f32_e32 v37, v37
	s_nop 0
	v_pk_mul_f32 v[34:35], v[36:37], v[34:35]
	s_nop 0
	v_pk_mul_f32 v[34:35], v[38:39], v[34:35]
	v_lshlrev_b32_e32 v36, 16, v83
	v_cvt_pk_bf16_f32 v34, v34, v35
	v_mul_f32_e32 v35, 0xbfb8aa3b, v36
	v_exp_f32_e32 v35, v35
	v_and_b32_e32 v37, 0xffff0000, v83
	v_add_f32_e32 v35, 1.0, v35
	v_rcp_f32_e32 v38, v35
	v_mul_f32_e32 v35, 0xbfb8aa3b, v37
	v_exp_f32_e32 v35, v35
	s_nop 0
	v_add_f32_e32 v35, 1.0, v35
	v_rcp_f32_e32 v39, v35
	s_nop 0
	v_pk_mul_f32 v[36:37], v[38:39], v[36:37]
	s_nop 0
	v_pk_mul_f32 v[36:37], v[40:41], v[36:37]
	s_nop 0
	v_cvt_pk_bf16_f32 v35, v36, v37
	global_store_dwordx2 v[130:131], v[34:35], off offset:368
	s_waitcnt vmcnt(15)
	v_lshlrev_b32_e32 v34, 16, v80
	v_and_b32_e32 v35, 0xffff0000, v80
	v_mul_f32_e32 v36, 0xbfb8aa3b, v34
	v_mul_f32_e32 v37, 0xbfb8aa3b, v35
	v_exp_f32_e32 v36, v36
	v_exp_f32_e32 v37, v37
	v_add_f32_e32 v36, 1.0, v36
	v_add_f32_e32 v37, 1.0, v37
	v_rcp_f32_e32 v36, v36
	v_rcp_f32_e32 v37, v37
	s_nop 0
	v_pk_mul_f32 v[34:35], v[36:37], v[34:35]
	s_nop 0
	v_pk_mul_f32 v[18:19], v[18:19], v[34:35]
	v_lshlrev_b32_e32 v34, 16, v81
	v_cvt_pk_bf16_f32 v18, v18, v19
	v_mul_f32_e32 v19, 0xbfb8aa3b, v34
	v_exp_f32_e32 v19, v19
	v_and_b32_e32 v35, 0xffff0000, v81
	v_add_f32_e32 v19, 1.0, v19
	v_rcp_f32_e32 v36, v19
	v_mul_f32_e32 v19, 0xbfb8aa3b, v35
	v_exp_f32_e32 v19, v19
	s_nop 0
	v_add_f32_e32 v19, 1.0, v19
	v_rcp_f32_e32 v37, v19
	s_nop 0
	v_pk_mul_f32 v[34:35], v[36:37], v[34:35]
	s_nop 0
	v_pk_mul_f32 v[20:21], v[20:21], v[34:35]
	s_nop 0
	v_cvt_pk_bf16_f32 v19, v20, v21
	global_store_dwordx2 v[130:131], v[18:19], off offset:384
	s_waitcnt vmcnt(15)
	v_lshlrev_b32_e32 v18, 16, v78
	v_and_b32_e32 v19, 0xffff0000, v78
	v_mul_f32_e32 v20, 0xbfb8aa3b, v18
	v_mul_f32_e32 v21, 0xbfb8aa3b, v19
	v_exp_f32_e32 v20, v20
	v_exp_f32_e32 v21, v21
	v_add_f32_e32 v20, 1.0, v20
	v_add_f32_e32 v21, 1.0, v21
	v_rcp_f32_e32 v20, v20
	v_rcp_f32_e32 v21, v21
	s_nop 0
	v_pk_mul_f32 v[18:19], v[20:21], v[18:19]
	s_nop 0
	v_pk_mul_f32 v[18:19], v[22:23], v[18:19]
	v_lshlrev_b32_e32 v20, 16, v79
	v_cvt_pk_bf16_f32 v18, v18, v19
	v_mul_f32_e32 v19, 0xbfb8aa3b, v20
	v_exp_f32_e32 v19, v19
	v_and_b32_e32 v21, 0xffff0000, v79
	v_add_f32_e32 v19, 1.0, v19
	v_rcp_f32_e32 v22, v19
	v_mul_f32_e32 v19, 0xbfb8aa3b, v21
	v_exp_f32_e32 v19, v19
	s_nop 0
	v_add_f32_e32 v19, 1.0, v19
	v_rcp_f32_e32 v23, v19
	s_nop 0
	v_pk_mul_f32 v[20:21], v[22:23], v[20:21]
	s_nop 0
	v_pk_mul_f32 v[20:21], v[24:25], v[20:21]
	v_pk_mul_f32 v[22:23], v[0:1], v[26:27] op_sel_hi:[0,1]
	v_cvt_pk_bf16_f32 v19, v20, v21
	global_store_dwordx2 v[130:131], v[18:19], off offset:400
	s_waitcnt vmcnt(15)
	v_lshlrev_b32_e32 v18, 16, v76
	v_and_b32_e32 v19, 0xffff0000, v76
	v_mul_f32_e32 v20, 0xbfb8aa3b, v18
	v_mul_f32_e32 v21, 0xbfb8aa3b, v19
	v_exp_f32_e32 v20, v20
	v_exp_f32_e32 v21, v21
	v_pk_mul_f32 v[24:25], v[0:1], v[28:29] op_sel_hi:[0,1]
	v_add_f32_e32 v20, 1.0, v20
	v_add_f32_e32 v21, 1.0, v21
	v_rcp_f32_e32 v20, v20
	v_rcp_f32_e32 v21, v21
	s_nop 0
	v_pk_mul_f32 v[18:19], v[20:21], v[18:19]
	s_nop 0
	v_pk_mul_f32 v[18:19], v[22:23], v[18:19]
	v_lshlrev_b32_e32 v20, 16, v77
	v_cvt_pk_bf16_f32 v18, v18, v19
	v_mul_f32_e32 v19, 0xbfb8aa3b, v20
	v_exp_f32_e32 v19, v19
	v_and_b32_e32 v21, 0xffff0000, v77
	v_add_f32_e32 v19, 1.0, v19
	v_rcp_f32_e32 v22, v19
	v_mul_f32_e32 v19, 0xbfb8aa3b, v21
	v_exp_f32_e32 v19, v19
	s_nop 0
	v_add_f32_e32 v19, 1.0, v19
	v_rcp_f32_e32 v23, v19
	s_nop 0
	v_pk_mul_f32 v[20:21], v[22:23], v[20:21]
	s_nop 0
	v_pk_mul_f32 v[20:21], v[24:25], v[20:21]
	v_pk_mul_f32 v[22:23], v[0:1], v[30:31] op_sel_hi:[0,1]
	v_cvt_pk_bf16_f32 v19, v20, v21
	global_store_dwordx2 v[130:131], v[18:19], off offset:416
	s_waitcnt vmcnt(15)
	v_lshlrev_b32_e32 v18, 16, v74
	v_and_b32_e32 v19, 0xffff0000, v74
	v_mul_f32_e32 v20, 0xbfb8aa3b, v18
	v_mul_f32_e32 v21, 0xbfb8aa3b, v19
	v_exp_f32_e32 v20, v20
	v_exp_f32_e32 v21, v21
	v_pk_mul_f32 v[24:25], v[0:1], v[32:33] op_sel_hi:[0,1]
	v_add_f32_e32 v20, 1.0, v20
	v_add_f32_e32 v21, 1.0, v21
	v_rcp_f32_e32 v20, v20
	v_rcp_f32_e32 v21, v21
	s_nop 0
	v_pk_mul_f32 v[18:19], v[20:21], v[18:19]
	s_nop 0
	v_pk_mul_f32 v[18:19], v[22:23], v[18:19]
	v_lshlrev_b32_e32 v20, 16, v75
	v_cvt_pk_bf16_f32 v18, v18, v19
	v_mul_f32_e32 v19, 0xbfb8aa3b, v20
	v_exp_f32_e32 v19, v19
	v_and_b32_e32 v21, 0xffff0000, v75
	v_add_f32_e32 v19, 1.0, v19
	v_rcp_f32_e32 v22, v19
	v_mul_f32_e32 v19, 0xbfb8aa3b, v21
	v_exp_f32_e32 v19, v19
	s_nop 0
	v_add_f32_e32 v19, 1.0, v19
	v_rcp_f32_e32 v23, v19
	s_nop 0
	v_pk_mul_f32 v[20:21], v[22:23], v[20:21]
	s_nop 0
	v_pk_mul_f32 v[20:21], v[24:25], v[20:21]
	s_nop 0
	v_cvt_pk_bf16_f32 v19, v20, v21
	global_store_dwordx2 v[130:131], v[18:19], off offset:432
	s_waitcnt vmcnt(15)
	v_lshlrev_b32_e32 v18, 16, v72
	v_and_b32_e32 v19, 0xffff0000, v72
	v_mul_f32_e32 v20, 0xbfb8aa3b, v18
	v_mul_f32_e32 v21, 0xbfb8aa3b, v19
	v_exp_f32_e32 v20, v20
	v_exp_f32_e32 v21, v21
	v_add_f32_e32 v20, 1.0, v20
	v_add_f32_e32 v21, 1.0, v21
	v_rcp_f32_e32 v20, v20
	v_rcp_f32_e32 v21, v21
	s_nop 0
	v_pk_mul_f32 v[18:19], v[20:21], v[18:19]
	s_nop 0
	v_pk_mul_f32 v[2:3], v[2:3], v[18:19]
	v_lshlrev_b32_e32 v18, 16, v73
	v_cvt_pk_bf16_f32 v2, v2, v3
	v_mul_f32_e32 v3, 0xbfb8aa3b, v18
	v_exp_f32_e32 v3, v3
	v_and_b32_e32 v19, 0xffff0000, v73
	v_add_f32_e32 v3, 1.0, v3
	v_rcp_f32_e32 v20, v3
	v_mul_f32_e32 v3, 0xbfb8aa3b, v19
	v_exp_f32_e32 v3, v3
	s_nop 0
	v_add_f32_e32 v3, 1.0, v3
	v_rcp_f32_e32 v21, v3
	s_nop 0
	v_pk_mul_f32 v[18:19], v[20:21], v[18:19]
	s_nop 0
	v_pk_mul_f32 v[4:5], v[4:5], v[18:19]
	s_nop 0
	v_cvt_pk_bf16_f32 v3, v4, v5
	global_store_dwordx2 v[130:131], v[2:3], off offset:448
	s_waitcnt vmcnt(15)
	v_lshlrev_b32_e32 v2, 16, v70
	v_and_b32_e32 v3, 0xffff0000, v70
	v_mul_f32_e32 v4, 0xbfb8aa3b, v2
	v_mul_f32_e32 v5, 0xbfb8aa3b, v3
	v_exp_f32_e32 v4, v4
	v_exp_f32_e32 v5, v5
	v_add_f32_e32 v4, 1.0, v4
	v_add_f32_e32 v5, 1.0, v5
	v_rcp_f32_e32 v4, v4
	v_rcp_f32_e32 v5, v5
	s_nop 0
	v_pk_mul_f32 v[2:3], v[4:5], v[2:3]
	s_nop 0
	v_pk_mul_f32 v[2:3], v[6:7], v[2:3]
	v_lshlrev_b32_e32 v4, 16, v71
	v_cvt_pk_bf16_f32 v2, v2, v3
	v_mul_f32_e32 v3, 0xbfb8aa3b, v4
	v_exp_f32_e32 v3, v3
	v_and_b32_e32 v5, 0xffff0000, v71
	v_add_f32_e32 v3, 1.0, v3
	v_rcp_f32_e32 v6, v3
	v_mul_f32_e32 v3, 0xbfb8aa3b, v5
	v_exp_f32_e32 v3, v3
	s_nop 0
	v_add_f32_e32 v3, 1.0, v3
	v_rcp_f32_e32 v7, v3
	s_nop 0
	v_pk_mul_f32 v[4:5], v[6:7], v[4:5]
	s_nop 0
	v_pk_mul_f32 v[4:5], v[8:9], v[4:5]
	v_pk_mul_f32 v[6:7], v[0:1], v[10:11] op_sel_hi:[0,1]
	v_cvt_pk_bf16_f32 v3, v4, v5
	global_store_dwordx2 v[130:131], v[2:3], off offset:464
	s_waitcnt vmcnt(15)
	v_lshlrev_b32_e32 v2, 16, v68
	v_and_b32_e32 v3, 0xffff0000, v68
	v_mul_f32_e32 v4, 0xbfb8aa3b, v2
	v_mul_f32_e32 v5, 0xbfb8aa3b, v3
	v_exp_f32_e32 v4, v4
	v_exp_f32_e32 v5, v5
	v_pk_mul_f32 v[8:9], v[0:1], v[12:13] op_sel_hi:[0,1]
	v_add_f32_e32 v4, 1.0, v4
	v_add_f32_e32 v5, 1.0, v5
	v_rcp_f32_e32 v4, v4
	v_rcp_f32_e32 v5, v5
	s_nop 0
	v_pk_mul_f32 v[2:3], v[4:5], v[2:3]
	s_nop 0
	v_pk_mul_f32 v[2:3], v[6:7], v[2:3]
	v_lshlrev_b32_e32 v4, 16, v69
	v_cvt_pk_bf16_f32 v2, v2, v3
	v_mul_f32_e32 v3, 0xbfb8aa3b, v4
	v_exp_f32_e32 v3, v3
	v_and_b32_e32 v5, 0xffff0000, v69
	v_add_f32_e32 v3, 1.0, v3
	v_rcp_f32_e32 v6, v3
	v_mul_f32_e32 v3, 0xbfb8aa3b, v5
	v_exp_f32_e32 v3, v3
	s_nop 0
	v_add_f32_e32 v3, 1.0, v3
	v_rcp_f32_e32 v7, v3
	s_nop 0
	v_pk_mul_f32 v[4:5], v[6:7], v[4:5]
	s_nop 0
	v_pk_mul_f32 v[4:5], v[8:9], v[4:5]
	v_pk_mul_f32 v[6:7], v[0:1], v[14:15] op_sel_hi:[0,1]
	v_cvt_pk_bf16_f32 v3, v4, v5
	global_store_dwordx2 v[130:131], v[2:3], off offset:480
	s_waitcnt vmcnt(15)
	v_lshlrev_b32_e32 v2, 16, v66
	v_and_b32_e32 v3, 0xffff0000, v66
	v_mul_f32_e32 v4, 0xbfb8aa3b, v2
	v_mul_f32_e32 v5, 0xbfb8aa3b, v3
	v_exp_f32_e32 v4, v4
	v_exp_f32_e32 v5, v5
	v_pk_mul_f32 v[8:9], v[0:1], v[16:17] op_sel_hi:[0,1]
	v_add_f32_e32 v4, 1.0, v4
	v_add_f32_e32 v5, 1.0, v5
	v_rcp_f32_e32 v4, v4
	v_rcp_f32_e32 v5, v5
	s_nop 0
	v_pk_mul_f32 v[2:3], v[4:5], v[2:3]
	s_nop 0
	v_pk_mul_f32 v[2:3], v[6:7], v[2:3]
	v_lshlrev_b32_e32 v4, 16, v67
	v_and_b32_e32 v5, 0xffff0000, v67
	v_cvt_pk_bf16_f32 v2, v2, v3
	v_mul_f32_e32 v3, 0xbfb8aa3b, v4
	v_mul_f32_e32 v0, 0xbfb8aa3b, v5
	v_exp_f32_e32 v3, v3
	v_exp_f32_e32 v0, v0
	v_add_f32_e32 v3, 1.0, v3
	v_add_f32_e32 v0, 1.0, v0
	v_rcp_f32_e32 v6, v3
	v_rcp_f32_e32 v7, v0
	s_nop 0
	v_pk_mul_f32 v[4:5], v[6:7], v[4:5]
	s_nop 0
	v_pk_mul_f32 v[4:5], v[8:9], v[4:5]
	s_nop 0
	v_cvt_pk_bf16_f32 v3, v4, v5
	global_store_dwordx2 v[130:131], v[2:3], off offset:496
	s_barrier

.LBB0_417:
	v_readlane_b32 s0, v255, 55
	v_readlane_b32 s1, v255, 56
	v_readlane_b32 s4, v255, 22
	s_add_i32 s4, s4, 2
	s_mul_i32 s4, s4, s80
	v_mov_b32_e32 v0, 0
	s_mov_b32 s5, 0
	s_nop 3

.Lp2a_ok_p:
	buffer_inv sc1
	s_waitcnt vmcnt(0)
	v_readlane_b32 s0, v255, 29
	v_readlane_b32 s88, v255, 24
	v_readlane_b32 s1, v255, 30
	s_add_u32 s10, s0, 0x12800000
	v_readlane_b32 s89, v255, 25
	s_addc_u32 s11, s1, 0
	s_mov_b64 s[12:13], s[88:89]
	s_mov_b64 s[8:9], s[88:89]
	s_mov_b64 s[0:1], s[88:89]
	s_mov_b64 s[6:7], s[88:89]
	v_readlane_b32 s4, v254, 29
	v_mbcnt_lo_u32_b32 v10, -1, 0
	v_mbcnt_hi_u32_b32 v10, -1, v10
	v_readlane_b32 s5, v254, 30
	v_add_u32_e32 v0, s83, v10
	s_mov_b32 s58, 0xf800000
	s_andn2_b64 vcc, exec, s[4:5]
	v_readfirstlane_b32 s4, v0
	s_cbranch_vccnz .LBB0_429
	v_lshlrev_b32_e32 v2, 4, v0
	v_add_u32_e32 v3, 0x2000, v2
	v_ashrrev_i32_e32 v4, 31, v3
	v_lshrrev_b32_e32 v4, 22, v4
	v_add_u32_e32 v4, v3, v4
	v_ashrrev_i32_e32 v4, 10, v4
	s_load_dwordx2 s[12:13], s[12:13], 0x98
	s_nop 0
	s_load_dwordx2 s[8:9], s[8:9], 0x98
	v_mul_i32_i24_e32 v5, 0x400, v4
	v_sub_u32_e32 v3, v3, v5
	v_lshrrev_b32_e32 v5, 4, v3
	v_bitop3_b32 v3, v5, v3, 32 bitop3:0x6c
	s_waitcnt lgkmcnt(0)
	s_add_u32 s28, s12, 0x3ac00000
	v_ashrrev_i32_e32 v5, 31, v3
	s_addc_u32 s29, s13, 0
	v_readlane_b32 s5, v255, 26
	v_lshrrev_b32_e32 v5, 26, v5
	s_add_u32 s5, s8, s5
	v_add_u32_e32 v5, v3, v5
	v_lshlrev_b32_e32 v7, 3, v4
	s_addc_u32 s8, s9, 0
	v_ashrrev_i32_e32 v6, 6, v5
	v_and_b32_e32 v7, -16, v7
	v_and_b32_e32 v5, 0xc0, v5
	s_add_u32 s30, s5, 0x7200000
	v_add_u32_e32 v7, v6, v7
	v_sub_u32_e32 v3, v3, v5
	s_addc_u32 s31, s8, 0
	v_and_b32_e32 v6, 3, v6
	s_mov_b32 s8, 0x7fffe0
	v_lshrrev_b32_e32 v8, 2, v7
	v_lshlrev_b32_e32 v9, 1, v7
	v_lshlrev_b32_e32 v4, 5, v4
	v_ashrrev_i16_sdwa v3, v244, sext(v3) dst_sel:DWORD dst_unused:UNUSED_PAD src0_sel:DWORD src1_sel:BYTE_0
	v_and_or_b32 v6, v7, s8, v6
	v_and_b32_e32 v8, 4, v8
	v_and_b32_e32 v9, 24, v9
	v_and_b32_e32 v4, 32, v4
	v_bfe_i32 v3, v3, 0, 16
	v_or3_b32 v6, v6, v8, v9
	v_add_lshl_u32 v3, v4, v3, 1
	v_lshl_add_u32 v178, v6, 9, v3
	v_lshl_add_u32 v180, v7, 9, v3
	v_bfe_i32 v3, v0, 27, 1
	v_lshrrev_b32_e32 v3, 22, v3
	v_add_u32_e32 v3, v2, v3
	v_and_b32_e32 v3, 0xfffffc00, v3
	v_sub_u32_e32 v2, v2, v3
	v_lshrrev_b32_e32 v3, 4, v2
	v_ashrrev_i32_e32 v5, 31, v0
	v_bitop3_b32 v2, v3, v2, 32 bitop3:0x6c
	v_lshrrev_b32_e32 v5, 26, v5
	v_ashrrev_i32_e32 v3, 31, v2
	v_add_u32_e32 v0, v0, v5
	v_lshrrev_b32_e32 v3, 26, v3
	v_ashrrev_i32_e32 v0, 6, v0
	v_add_u32_e32 v3, v2, v3
	v_lshlrev_b32_e32 v5, 3, v0
	v_ashrrev_i32_e32 v4, 6, v3
	v_and_b32_e32 v5, -16, v5
	v_and_b32_e32 v3, 0xc0, v3
	s_ashr_i32 s5, s4, 6
	v_add_u32_e32 v5, v4, v5
	v_and_b32_e32 v4, 3, v4
	v_sub_u32_e32 v2, v2, v3
	s_ashr_i32 s18, s4, 8
	s_lshl_b32 s34, s5, 10
	v_and_or_b32 v4, v5, s8, v4
	v_lshrrev_b32_e32 v6, 2, v5
	v_lshlrev_b32_e32 v7, 1, v5
	v_lshlrev_b32_e32 v0, 5, v0
	v_ashrrev_i16_sdwa v2, v244, sext(v2) dst_sel:DWORD dst_unused:UNUSED_PAD src0_sel:DWORD src1_sel:BYTE_0
	v_readlane_b32 s8, v254, 35
	v_and_b32_e32 v6, 4, v6
	v_and_b32_e32 v7, 24, v7
	v_and_b32_e32 v0, 32, v0
	v_bfe_i32 v2, v2, 0, 16
	v_readlane_b32 s9, v254, 36
	s_add_u32 s8, s30, s8
	v_or3_b32 v4, v4, v6, v7
	v_add_lshl_u32 v2, v0, v2, 1
	s_addc_u32 s9, s31, s9
	s_add_i32 s35, s34, 0
	v_lshl_add_u32 v0, v4, 9, v2
	s_add_i32 m0, s35, 0x10000
	v_lshl_add_u32 v182, v5, 9, v2
	global_load_lds_dwordx4 v0, s[8:9]
	s_add_i32 m0, s35, 0x12000
	s_add_u32 s12, s8, 0x10000
	global_load_lds_dwordx4 v178, s[8:9]
	s_addc_u32 s13, s9, 0
	s_add_i32 m0, s35, 0x14000
	v_mov_b32_e32 v179, v1
	global_load_lds_dwordx4 v0, s[12:13]
	s_add_i32 m0, s35, 0x16000
	v_mov_b32_e32 v183, v1
	global_load_lds_dwordx4 v178, s[12:13]
	v_readlane_b32 s12, v254, 31
	v_readlane_b32 s13, v254, 32
	s_add_u32 s12, s28, s12
	s_addc_u32 s13, s29, s13
	s_add_i32 s36, s35, 0x2000
	s_mov_b32 m0, s35
	s_add_u32 s14, s12, 0x10000
	global_load_lds_dwordx4 v182, s[12:13]
	s_mov_b32 m0, s36
	s_addc_u32 s15, s13, 0
	s_add_i32 s37, s35, 0x4000
	global_load_lds_dwordx4 v180, s[12:13]
	s_mov_b32 m0, s37
	s_add_i32 s38, s35, 0x6000
	global_load_lds_dwordx4 v182, s[14:15]
	s_mov_b32 m0, s38
	v_mov_b32_e32 v181, v1
	global_load_lds_dwordx4 v180, s[14:15]
	s_load_dwordx2 s[16:17], s[0:1], 0x60
	s_nop 0
	s_load_dwordx2 s[0:1], s[6:7], 0x98
	s_cmp_eq_u32 s18, 1
	v_lshl_add_u64 v[8:9], s[8:9], 0, v[0:1]
	v_lshl_add_u64 v[6:7], s[8:9], 0, v[178:179]
	v_lshl_add_u64 v[2:3], s[12:13], 0, v[182:183]
	s_cselect_b64 s[14:15], -1, 0
	s_cmp_lg_u32 s18, 1
	v_lshl_add_u64 v[4:5], s[12:13], 0, v[180:181]
	s_cbranch_scc1 .LBB0_420
	s_barrier
